# v5 plus compact interleaved GELU epilogue and branch trampolines
# speedup vs baseline: 1.0137x; 1.0010x over previous
; #define PG8_STAGE(bufoff, gbase, voff) do { _Pragma("unroll") for (int _i = 0; _i < 2; ++_i) \
;         __builtin_amdgcn_global_load_lds((const unsigned*)((const char*)(gbase) + (voff)[_i]), (LAS unsigned*)(lds + (bufoff) + ldsw + _i * 8192), 16, 0, 0); } while (0)
; #define PG8_BAR __builtin_amdgcn_s_barrier()
; template <class Epi>
; __device__ __forceinline__ void gemm_phase(LAS unsigned char* lds, const Gemm g, const StaticOrder& S, const Epi& E, const int tidx) {
;     ...
;     for (;;) {
;         const bool has_next = S.next(ui + 1, nxt);
;         const char* nA = has_next ? (const char*)g.A + (size_t)nxt.pm * tstep : cA; const char* nB = has_next ? (const char*)g.Bt + (size_t)nxt.pn * tstep : cB;
;         for (int t = 0; t < nt; t += 2) {
;             const bool last = (t == nt - 2);
;             const char* a1 = cA + (size_t)(t + 1) * kstep;
;             const char* a2 = last ? nA : cA + (size_t)(t + 2) * kstep; const char* b2 = last ? nB : cB + (size_t)(t + 2) * kstep;
;             const char* a3 = a2 + kstep; const char* b3 = b2 + kstep;
;             PG8_LDB(B0, 0, 0); PG8_SCHED; PG8_LDA(At, 0, 0); PG8_STAGE(PG8_SA(1, 1), a1 + hstep, voffA);
;             PG8_WAIT_L(8); PG8_BAR; PG8_WAIT_L(0); PG8_MMA(0, 0, At, B0); PG8_BAR; PG8_SCHED;
;             PG8_LDB(B1, 0, 1); PG8_STAGE(PG8_SB(0, 0), b2, voffB);
;             PG8_BAR; PG8_WAIT_L(0); PG8_MMA(0, 1, At, B1); PG8_BAR;
;             PG8_LDA(At, 0, 1); PG8_STAGE(PG8_SA(0, 0), a2, voffA);
;             PG8_BAR; PG8_WAIT_L(0); PG8_MMA(1, 0, At, B0); PG8_BAR; PG8_SCHED;
;             PG8_STAGE(PG8_SB(0, 1), b2 + hstep, voffB);
;             PG8_WAIT_V(6); PG8_BAR; PG8_MMA(1, 1, At, B1); PG8_BAR;
;             PG8_LDB(B0, 1, 0); PG8_SCHED; PG8_LDA(At, 1, 0); PG8_STAGE(PG8_SA(0, 1), a2 + hstep, voffA);
;             PG8_WAIT_L(8); PG8_BAR; PG8_WAIT_L(0); PG8_MMA(0, 0, At, B0); PG8_BAR; PG8_SCHED;
;             PG8_LDB(B1, 1, 1); PG8_STAGE(PG8_SB(1, 0), b3, voffB);
;             PG8_BAR; PG8_WAIT_L(0); PG8_MMA(0, 1, At, B1); PG8_BAR;
;             PG8_LDA(At, 1, 1); PG8_STAGE(PG8_SA(1, 0), a3, voffA);
;             PG8_BAR; PG8_WAIT_L(0); PG8_MMA(1, 0, At, B0); PG8_BAR; PG8_SCHED;
;             PG8_STAGE(PG8_SB(1, 1), b3 + hstep, voffB);
;             PG8_WAIT_V(6); PG8_BAR; PG8_MMA(1, 1, At, B1); PG8_BAR;
;         }
;         E(acc, cur, wr, wc, fr, fq);
;         if (!has_next) break;
.Ltr_LBB0_1810:
	s_branch .LBB0_1810

; __device__ __forceinline__ f32x2 gelu_pk(f32x2 v) {
;     const f32x2 av = __builtin_elementwise_abs(v), d = av * 0.2316418882f + 1.0f;
;     f32x2 t; t.x = __builtin_amdgcn_rcpf(d.x); t.y = __builtin_amdgcn_rcpf(d.y);
;     f32x2 q = t * 0.5307027145f + (-0.7265760135f); q = q * t + 0.7107068705f; q = q * t + (-0.142248368f); q = q * t + 0.127414796f; q = q * t;
;     const f32x2 s = (v * v) * (-0.72134752044f);
;     f32x2 e; e.x = __builtin_amdgcn_exp2f(s.x); e.y = __builtin_amdgcn_exp2f(s.y);
;     const f32x2 m = v * (q * e), r = v - m;
;     f32x2 o; o.x = v.x < 0.f ? m.x : r.x; o.y = v.y < 0.f ? m.y : r.y; return o;
; }
;     __device__ __forceinline__ void epi_proj(const f32x4 (&acc)[2][2][4][2], const pg8::Unit& u, int wr, int wc, int fr, int fq) const {
;     ...
;             for (int m = 0; m < 4; ++m) rstd8[ai][m] = rs[row0 + ai * 128 + m * 16];
; #pragma unroll
;         for (int ai = 0; ai < 2; ++ai)
; #pragma unroll
;             for (int m = 0; m < 4; ++m) rstd8[ai][m] = rsqrtf(rstd8[ai][m] * (1.0f / 1024.0f) + EPS);
; #pragma unroll
;         for (int ai = 0; ai < 2; ++ai)
; #pragma unroll
;             for (int m = 0; m < 4; ++m) {
;                 const int r = row0 + ai * 128 + m * 16;
;                     const float rstd = rstd8[ai][m];
;                     if (u.pn == 32) {
;                         if (wc == 0 && fq < 2) {
;                             const f32x4 v0 = acc[ai][0][m][0] * rstd, v1 = acc[ai][0][m][1] * rstd;
;                             float o8[8] = {v0[0], v0[1], v0[2], v0[3], v1[0], v1[1], v1[2], v1[3]};
; #pragma unroll
;                             for (int h = 0; h < 8; ++h) {
;                                 if (fq == 0) o8[h] = sigmoidf_(o8[h]);
;                                 else { const float xx = o8[h] + dt_bias[l * 8 + h]; const float sp = xx > 20.f ? xx : log1pf(__expf(xx)); o8[h] = -__expf(a_log[l * 8 + h]) * sp; }
;                             }
;                             float* dst = bg + (size_t)r * 16 + 8 * fq;
;                             *(f32x4*)dst = (f32x4){o8[0], o8[1], o8[2], o8[3]}; *(f32x4*)(dst + 4) = (f32x4){o8[4], o8[5], o8[6], o8[7]};
;                         }
;                     } else {
;                         const int slot = u.pn >> 2;
;                         bf16_t* rowp = act + (size_t)slot * SLOT_EL + (size_t)r * 1024 + (colt & 1023);
; #pragma unroll
.Lepi_gelu:
	s_mov_b32 s14, 0x3e6d3388
	s_mov_b32 s15, 0x3f07dc22
	s_mov_b32 s20, 0xbf38aa3b
	v_mov_b32_e32 v188, 0xbf3a00e3
	v_mov_b32_e32 v189, 0x3f35f0e3
	v_mov_b32_e32 v190, 0xbe11a98e
	v_mov_b32_e32 v191, 0x3e027906
	v_readlane_b32 s6, v254, 34
	v_readlane_b32 s7, v254, 35
	s_mov_b64 s[0:1], s[6:7]
	s_load_dwordx2 s[4:5], s[0:1], 0xb0
	s_mov_b64 s[0:1], s[6:7]
	s_mov_b64 s[0:1], s[6:7]
	s_mov_b64 s[0:1], s[6:7]
	s_mov_b64 s[0:1], s[6:7]
	v_lshl_add_u32 v136, s13, 8, v239
	v_ashrrev_i32_e32 v137, 31, v136
	s_mov_b64 s[0:1], s[6:7]
	s_waitcnt lgkmcnt(0)
	v_lshl_add_u64 v[128:129], v[136:137], 2, s[66:67]
	global_load_dword v130, v[128:129], off
	global_load_dword v131, v[128:129], off offset:64
	global_load_dword v132, v[128:129], off offset:128
	global_load_dword v133, v[128:129], off offset:192
	global_load_dword v134, v[128:129], off offset:512
	global_load_dword v135, v[128:129], off offset:576
	global_load_dword v139, v[128:129], off offset:640
	s_nop 0
	global_load_dword v128, v[128:129], off offset:704
	s_mov_b32 s0, 0x800000
	v_lshl_or_b32 v152, s88, 8, v245
	v_and_b32_e32 v152, 0x3ff, v152
	v_ashrrev_i32_e32 v153, 31, v152
	v_lshl_add_u64 v[152:153], v[152:153], 1, s[4:5]
	v_or_b32_e32 v146, 16, v136
	v_or_b32_e32 v142, 32, v136
	v_or_b32_e32 v140, 48, v136
	v_lshlrev_b64 v[136:137], 11, v[136:137]
	v_ashrrev_i32_e32 v147, 31, v146
	v_lshlrev_b64 v[146:147], 11, v[146:147]
	v_ashrrev_i32_e32 v143, 31, v142
	v_lshlrev_b64 v[142:143], 11, v[142:143]
	v_ashrrev_i32_e32 v141, 31, v140
	v_lshlrev_b64 v[140:141], 11, v[140:141]
	s_waitcnt vmcnt(0)
	v_fmamk_f32 v129, v130, 0x3a800000, v237
	v_cmp_gt_f32_e32 vcc, s0, v129
	v_mul_f32_e32 v130, 0x4b800000, v129
	v_fmamk_f32 v128, v128, 0x3a800000, v237
	v_cndmask_b32_e32 v129, v129, v130, vcc
	v_rsq_f32_e32 v129, v129
	s_nop 0
	v_mul_f32_e32 v130, 0x45800000, v129
	v_cndmask_b32_e32 v150, v129, v130, vcc
	v_fmamk_f32 v129, v131, 0x3a800000, v237
	v_cmp_gt_f32_e32 vcc, s0, v129
	v_mul_f32_e32 v130, 0x4b800000, v129
	v_pk_mul_f32 v[154:155], v[118:119], v[150:151] op_sel_hi:[1,0]
	v_cndmask_b32_e32 v129, v129, v130, vcc
	v_rsq_f32_e32 v129, v129
	v_pk_mul_f32 v[156:157], v[116:117], v[150:151] op_sel_hi:[1,0]
	v_pk_mul_f32 v[158:159], v[114:115], v[150:151] op_sel_hi:[1,0]
	v_pk_mul_f32 v[160:161], v[112:113], v[150:151] op_sel_hi:[1,0]
	v_mul_f32_e32 v130, 0x45800000, v129
	v_cndmask_b32_e32 v148, v129, v130, vcc
	v_fmamk_f32 v129, v132, 0x3a800000, v237
	v_cmp_gt_f32_e32 vcc, s0, v129
	v_mul_f32_e32 v130, 0x4b800000, v129
	v_cndmask_b32_e32 v129, v129, v130, vcc
	v_rsq_f32_e32 v129, v129
	v_mul_f32_e32 v130, 0x45800000, v129
	v_cndmask_b32_e32 v144, v129, v130, vcc
	v_fmamk_f32 v129, v133, 0x3a800000, v237
	v_cmp_gt_f32_e32 vcc, s0, v129
	v_mul_f32_e32 v130, 0x4b800000, v129
	v_cndmask_b32_e32 v129, v129, v130, vcc
	v_rsq_f32_e32 v129, v129
	v_mul_f32_e32 v130, 0x45800000, v129
	v_cndmask_b32_e32 v138, v129, v130, vcc
	v_fmamk_f32 v129, v134, 0x3a800000, v237
	v_cmp_gt_f32_e32 vcc, s0, v129
	v_mul_f32_e32 v130, 0x4b800000, v129
	v_and_b32_e32 v164, 0x7fffffff, v156
	v_and_b32_e32 v167, 0x7fffffff, v160
	v_and_b32_e32 v170, 0x7fffffff, v157
	v_and_b32_e32 v173, 0x7fffffff, v161
	v_and_b32_e32 v176, 0x7fffffff, v154
	v_and_b32_e32 v179, 0x7fffffff, v158
	v_and_b32_e32 v182, 0x7fffffff, v155
	v_and_b32_e32 v185, 0x7fffffff, v159
	v_mul_f32_e32 v165, v156, v156
	v_mul_f32_e32 v168, v160, v160
	v_mul_f32_e32 v171, v157, v157
	v_mul_f32_e32 v174, v161, v161
	v_mul_f32_e32 v177, v154, v154
	v_mul_f32_e32 v180, v158, v158
	v_mul_f32_e32 v183, v155, v155
	v_mul_f32_e32 v186, v159, v159
	v_fma_f32 v164, v164, s14, 1.0
	v_fma_f32 v167, v167, s14, 1.0
	v_fma_f32 v170, v170, s14, 1.0
	v_fma_f32 v173, v173, s14, 1.0
	v_fma_f32 v176, v176, s14, 1.0
	v_fma_f32 v179, v179, s14, 1.0
	v_fma_f32 v182, v182, s14, 1.0
	v_fma_f32 v185, v185, s14, 1.0
	v_mul_f32_e32 v165, s20, v165
	v_mul_f32_e32 v168, s20, v168
	v_mul_f32_e32 v171, s20, v171
	v_mul_f32_e32 v174, s20, v174
	v_mul_f32_e32 v177, s20, v177
	v_mul_f32_e32 v180, s20, v180
	v_mul_f32_e32 v183, s20, v183
	v_mul_f32_e32 v186, s20, v186
	v_rcp_f32_e32 v164, v164
	v_rcp_f32_e32 v167, v167
	v_rcp_f32_e32 v170, v170
	v_rcp_f32_e32 v173, v173
	v_rcp_f32_e32 v176, v176
	v_rcp_f32_e32 v179, v179
	v_rcp_f32_e32 v182, v182
	v_rcp_f32_e32 v185, v185
	s_nop 0
	v_exp_f32_e32 v165, v165
	v_exp_f32_e32 v168, v168
	v_exp_f32_e32 v171, v171
	v_exp_f32_e32 v174, v174
	v_exp_f32_e32 v177, v177
	v_exp_f32_e32 v180, v180
	v_exp_f32_e32 v183, v183
	v_exp_f32_e32 v186, v186
	s_nop 0
	v_fma_f32 v166, v164, s15, v188
	v_fma_f32 v169, v167, s15, v188
	v_fma_f32 v172, v170, s15, v188
	v_fma_f32 v175, v173, s15, v188
	v_fma_f32 v178, v176, s15, v188
	v_fma_f32 v181, v179, s15, v188
	v_fma_f32 v184, v182, s15, v188
	v_fma_f32 v187, v185, s15, v188
	v_fma_f32 v166, v166, v164, v189
	v_fma_f32 v169, v169, v167, v189
	v_fma_f32 v172, v172, v170, v189
	v_fma_f32 v175, v175, v173, v189
	v_fma_f32 v178, v178, v176, v189
	v_fma_f32 v181, v181, v179, v189
	v_fma_f32 v184, v184, v182, v189
	v_fma_f32 v187, v187, v185, v189
	v_fma_f32 v166, v166, v164, v190
	v_fma_f32 v169, v169, v167, v190
	v_fma_f32 v172, v172, v170, v190
	v_fma_f32 v175, v175, v173, v190
	v_fma_f32 v178, v178, v176, v190
	v_fma_f32 v181, v181, v179, v190
	v_fma_f32 v184, v184, v182, v190
	v_fma_f32 v187, v187, v185, v190
	v_fma_f32 v166, v166, v164, v191
	v_fma_f32 v169, v169, v167, v191
	v_fma_f32 v172, v172, v170, v191
	v_fma_f32 v175, v175, v173, v191
	v_fma_f32 v178, v178, v176, v191
	v_fma_f32 v181, v181, v179, v191
	v_fma_f32 v184, v184, v182, v191
	v_fma_f32 v187, v187, v185, v191
	v_mul_f32_e32 v166, v166, v164
; __device__ __forceinline__ unsigned cvt_pk_bf16(float lo, float hi) { const f32x2 v = {lo, hi}; const bf16v2_t b = __builtin_convertvector(v, bf16v2_t); return __builtin_bit_cast(unsigned, b); }
; __device__ __forceinline__ f32x2 gelu_pk(f32x2 v) {
;     const f32x2 av = __builtin_elementwise_abs(v), d = av * 0.2316418882f + 1.0f;
;     f32x2 t; t.x = __builtin_amdgcn_rcpf(d.x); t.y = __builtin_amdgcn_rcpf(d.y);
;     f32x2 q = t * 0.5307027145f + (-0.7265760135f); q = q * t + 0.7107068705f; q = q * t + (-0.142248368f); q = q * t + 0.127414796f; q = q * t;
;     const f32x2 s = (v * v) * (-0.72134752044f);
;     f32x2 e; e.x = __builtin_amdgcn_exp2f(s.x); e.y = __builtin_amdgcn_exp2f(s.y);
;     const f32x2 m = v * (q * e), r = v - m;
;     f32x2 o; o.x = v.x < 0.f ? m.x : r.x; o.y = v.y < 0.f ? m.y : r.y; return o;
; }
;     __device__ __forceinline__ void epi_proj(const f32x4 (&acc)[2][2][4][2], const pg8::Unit& u, int wr, int wc, int fr, int fq) const {
;     ...
;                         const int slot = u.pn >> 2;
;                         bf16_t* rowp = act + (size_t)slot * SLOT_EL + (size_t)r * 1024 + (colt & 1023);
; #pragma unroll
;                         for (int bj = 0; bj < 2; ++bj) {
;                             f32x4 v0 = acc[ai][bj][m][0] * rstd, v1 = acc[ai][bj][m][1] * rstd;
;                             if (slot < 2) {
;                                 f32x2 a = gelu_pk((f32x2){v0[0], v0[1]}), b = gelu_pk((f32x2){v0[2], v0[3]}), c = gelu_pk((f32x2){v1[0], v1[1]}), d = gelu_pk((f32x2){v1[2], v1[3]});
;                                 v0 = (f32x4){a.x, a.y, b.x, b.y}; v1 = (f32x4){c.x, c.y, d.x, d.y};
;                             } else if (slot == 5) {
; #pragma unroll
;                                 for (int j = 0; j < 4; ++j) { v0[j] = siluf_(v0[j]); v1[j] = siluf_(v1[j]); }
;                             } else if (slot >= 6) {
; #pragma unroll
;                                 for (int j = 0; j < 4; ++j) { v0[j] = sigmoidf_(v0[j]); v1[j] = sigmoidf_(v1[j]); }
;                             }
;                             u32x4 w; w.x = cvt_pk_bf16(v0[0], v0[1]); w.y = cvt_pk_bf16(v0[2], v0[3]); w.z = cvt_pk_bf16(v1[0], v1[1]); w.w = cvt_pk_bf16(v1[2], v1[3]);
;                             *(u32x4*)(rowp + bj * 128) = w;
	v_mul_f32_e32 v169, v169, v167
	v_mul_f32_e32 v172, v172, v170
	v_mul_f32_e32 v175, v175, v173
	v_mul_f32_e32 v178, v178, v176
	v_mul_f32_e32 v181, v181, v179
	v_mul_f32_e32 v184, v184, v182
	v_mul_f32_e32 v187, v187, v185
	v_mul_f32_e32 v166, v166, v165
	v_mul_f32_e32 v169, v169, v168
	v_mul_f32_e32 v172, v172, v171
	v_mul_f32_e32 v175, v175, v174
	v_mul_f32_e32 v178, v178, v177
	v_mul_f32_e32 v181, v181, v180
	v_mul_f32_e32 v184, v184, v183
	v_mul_f32_e32 v187, v187, v186
	v_mul_f32_e32 v166, v156, v166
	v_mul_f32_e32 v169, v160, v169
	v_mul_f32_e32 v172, v157, v172
	v_mul_f32_e32 v175, v161, v175
	v_mul_f32_e32 v178, v154, v178
	v_mul_f32_e32 v181, v158, v181
	v_mul_f32_e32 v184, v155, v184
	v_mul_f32_e32 v187, v159, v187
	v_sub_f32_e32 v165, v156, v166
	v_sub_f32_e32 v168, v160, v169
	v_sub_f32_e32 v171, v157, v172
	v_sub_f32_e32 v174, v161, v175
	v_sub_f32_e32 v177, v154, v178
	v_sub_f32_e32 v180, v158, v181
	v_sub_f32_e32 v183, v155, v184
	v_sub_f32_e32 v186, v159, v187
	v_cmp_gt_f32_e64 s[100:101], 0, v156
	s_nop 1
	v_cndmask_b32_e64 v156, v165, v166, s[100:101]
	v_cmp_gt_f32_e64 s[100:101], 0, v160
	s_nop 1
	v_cndmask_b32_e64 v160, v168, v169, s[100:101]
	v_cmp_gt_f32_e64 s[100:101], 0, v157
	s_nop 1
	v_cndmask_b32_e64 v157, v171, v172, s[100:101]
	v_cmp_gt_f32_e64 s[100:101], 0, v161
	s_nop 1
	v_cndmask_b32_e64 v161, v174, v175, s[100:101]
	v_cmp_gt_f32_e64 s[100:101], 0, v154
	s_nop 1
	v_cndmask_b32_e64 v154, v177, v178, s[100:101]
	v_cmp_gt_f32_e64 s[100:101], 0, v158
	s_nop 1
	v_cndmask_b32_e64 v158, v180, v181, s[100:101]
	v_cmp_gt_f32_e64 s[100:101], 0, v155
	s_nop 1
	v_cndmask_b32_e64 v155, v183, v184, s[100:101]
	v_cmp_gt_f32_e64 s[100:101], 0, v159
	s_nop 1
	v_cndmask_b32_e64 v159, v186, v187, s[100:101]
	v_cndmask_b32_e32 v129, v129, v130, vcc
	v_rsq_f32_e32 v129, v129
	v_mov_b32_e32 v162, v154
	v_mov_b32_e32 v163, v155
	v_mul_f32_e32 v130, 0x45800000, v129
	v_cndmask_b32_e32 v134, v129, v130, vcc
	v_fmamk_f32 v129, v135, 0x3a800000, v237
	v_cmp_gt_f32_e32 vcc, s0, v129
	v_mul_f32_e32 v130, 0x4b800000, v129
	v_cvt_pk_bf16_f32 v154, v156, v157
	v_cndmask_b32_e32 v129, v129, v130, vcc
	v_rsq_f32_e32 v129, v129
	v_cvt_pk_bf16_f32 v155, v162, v163
	v_cvt_pk_bf16_f32 v156, v160, v161
	v_cvt_pk_bf16_f32 v157, v158, v159
	v_mul_f32_e32 v130, 0x45800000, v129
	v_cndmask_b32_e32 v132, v129, v130, vcc
	v_fmamk_f32 v129, v139, 0x3a800000, v237
	v_cmp_gt_f32_e32 vcc, s0, v129
	v_mul_f32_e32 v130, 0x4b800000, v129
	v_pk_mul_f32 v[158:159], v[122:123], v[150:151] op_sel_hi:[1,0]
	v_cndmask_b32_e32 v129, v129, v130, vcc
	v_rsq_f32_e32 v129, v129
	v_and_b32_e32 v164, 0x7fffffff, v158
	v_and_b32_e32 v167, 0x7fffffff, v159
	v_mul_f32_e32 v165, v158, v158
	v_mul_f32_e32 v168, v159, v159
	v_fma_f32 v164, v164, s14, 1.0
	v_fma_f32 v167, v167, s14, 1.0
	v_mul_f32_e32 v165, s20, v165
	v_mul_f32_e32 v168, s20, v168
	v_rcp_f32_e32 v164, v164
	v_rcp_f32_e32 v167, v167
	s_nop 0
	v_exp_f32_e32 v165, v165
	v_exp_f32_e32 v168, v168
	s_nop 0
	v_fma_f32 v166, v164, s15, v188
	v_fma_f32 v169, v167, s15, v188
	v_fma_f32 v166, v166, v164, v189
	v_fma_f32 v169, v169, v167, v189
	v_fma_f32 v166, v166, v164, v190
	v_fma_f32 v169, v169, v167, v190
	v_fma_f32 v166, v166, v164, v191
	v_fma_f32 v169, v169, v167, v191
	v_mul_f32_e32 v166, v166, v164
	v_mul_f32_e32 v169, v169, v167
	v_mul_f32_e32 v166, v166, v165
	v_mul_f32_e32 v169, v169, v168
	v_mul_f32_e32 v166, v158, v166
	v_mul_f32_e32 v169, v159, v169
	v_sub_f32_e32 v165, v158, v166
	v_sub_f32_e32 v168, v159, v169
	v_cmp_gt_f32_e64 s[100:101], 0, v158
	s_nop 1
	v_cndmask_b32_e64 v158, v165, v166, s[100:101]
	v_cmp_gt_f32_e64 s[100:101], 0, v159
	s_nop 1
	v_cndmask_b32_e64 v159, v168, v169, s[100:101]
	v_mul_f32_e32 v130, 0x45800000, v129
	v_cndmask_b32_e32 v130, v129, v130, vcc
	v_cmp_gt_f32_e32 vcc, s0, v128
	s_lshr_b32 s0, s88, 2
	s_mul_i32 s0, s0, 0x4080000
	s_add_u32 s0, s0, 0x8d80000
	s_mov_b32 s1, 0
	v_lshl_add_u64 v[152:153], v[152:153], 0, s[0:1]
	v_lshl_add_u64 v[136:137], v[152:153], 0, v[136:137]
	global_store_dwordx4 v[136:137], v[154:157], off
	v_mul_f32_e32 v129, 0x4b800000, v128
	v_cndmask_b32_e32 v128, v128, v129, vcc
	v_pk_mul_f32 v[154:155], v[126:127], v[150:151] op_sel_hi:[1,0]
	v_pk_mul_f32 v[156:157], v[124:125], v[150:151] op_sel_hi:[1,0]
	v_pk_mul_f32 v[150:151], v[120:121], v[150:151] op_sel_hi:[1,0]
	v_and_b32_e32 v164, 0x7fffffff, v156
	v_and_b32_e32 v167, 0x7fffffff, v150
	v_and_b32_e32 v170, 0x7fffffff, v157
	v_and_b32_e32 v173, 0x7fffffff, v151
	v_and_b32_e32 v176, 0x7fffffff, v154
	v_and_b32_e32 v179, 0x7fffffff, v155
	v_mul_f32_e32 v165, v156, v156
	v_mul_f32_e32 v168, v150, v150
	v_mul_f32_e32 v171, v157, v157
	v_mul_f32_e32 v174, v151, v151
	v_mul_f32_e32 v177, v154, v154
	v_mul_f32_e32 v180, v155, v155
	v_fma_f32 v164, v164, s14, 1.0
	v_fma_f32 v167, v167, s14, 1.0
	v_fma_f32 v170, v170, s14, 1.0
	v_fma_f32 v173, v173, s14, 1.0
	v_fma_f32 v176, v176, s14, 1.0
	v_fma_f32 v179, v179, s14, 1.0
	v_mul_f32_e32 v165, s20, v165
	v_mul_f32_e32 v168, s20, v168
	v_mul_f32_e32 v171, s20, v171
	v_mul_f32_e32 v174, s20, v174
	v_mul_f32_e32 v177, s20, v177
	v_mul_f32_e32 v180, s20, v180
	v_rcp_f32_e32 v164, v164
	v_rcp_f32_e32 v167, v167
	v_rcp_f32_e32 v170, v170
	v_rcp_f32_e32 v173, v173
	v_rcp_f32_e32 v176, v176
	v_rcp_f32_e32 v179, v179
	s_nop 0
	v_exp_f32_e32 v165, v165
	v_exp_f32_e32 v168, v168
	v_exp_f32_e32 v171, v171
	v_exp_f32_e32 v174, v174
	v_exp_f32_e32 v177, v177
	v_exp_f32_e32 v180, v180
	s_nop 0
	v_fma_f32 v166, v164, s15, v188
	v_fma_f32 v169, v167, s15, v188
	v_fma_f32 v172, v170, s15, v188
	v_fma_f32 v175, v173, s15, v188
	v_fma_f32 v178, v176, s15, v188
; __device__ __forceinline__ unsigned cvt_pk_bf16(float lo, float hi) { const f32x2 v = {lo, hi}; const bf16v2_t b = __builtin_convertvector(v, bf16v2_t); return __builtin_bit_cast(unsigned, b); }
; __device__ __forceinline__ float sigmoidf_(float x) { return __builtin_amdgcn_rcpf(1.0f + __builtin_amdgcn_exp2f(x * -1.44269504089f)); }
; __device__ __forceinline__ float siluf_(float x) { return x * __builtin_amdgcn_rcpf(1.0f + __builtin_amdgcn_exp2f(x * -1.44269504089f)); }
; __device__ __forceinline__ f32x2 gelu_pk(f32x2 v) {
;     const f32x2 av = __builtin_elementwise_abs(v), d = av * 0.2316418882f + 1.0f;
;     f32x2 t; t.x = __builtin_amdgcn_rcpf(d.x); t.y = __builtin_amdgcn_rcpf(d.y);
;     f32x2 q = t * 0.5307027145f + (-0.7265760135f); q = q * t + 0.7107068705f; q = q * t + (-0.142248368f); q = q * t + 0.127414796f; q = q * t;
;     const f32x2 s = (v * v) * (-0.72134752044f);
;     f32x2 e; e.x = __builtin_amdgcn_exp2f(s.x); e.y = __builtin_amdgcn_exp2f(s.y);
;     const f32x2 m = v * (q * e), r = v - m;
;     f32x2 o; o.x = v.x < 0.f ? m.x : r.x; o.y = v.y < 0.f ? m.y : r.y; return o;
; }
;     __device__ __forceinline__ void epi_proj(const f32x4 (&acc)[2][2][4][2], const pg8::Unit& u, int wr, int wc, int fr, int fq) const {
;     ...
; #pragma unroll
;                         for (int bj = 0; bj < 2; ++bj) {
;                             f32x4 v0 = acc[ai][bj][m][0] * rstd, v1 = acc[ai][bj][m][1] * rstd;
;                             if (slot < 2) {
;                                 f32x2 a = gelu_pk((f32x2){v0[0], v0[1]}), b = gelu_pk((f32x2){v0[2], v0[3]}), c = gelu_pk((f32x2){v1[0], v1[1]}), d = gelu_pk((f32x2){v1[2], v1[3]});
;                                 v0 = (f32x4){a.x, a.y, b.x, b.y}; v1 = (f32x4){c.x, c.y, d.x, d.y};
;                             } else if (slot == 5) {
; #pragma unroll
;                                 for (int j = 0; j < 4; ++j) { v0[j] = siluf_(v0[j]); v1[j] = siluf_(v1[j]); }
;                             } else if (slot >= 6) {
; #pragma unroll
;                                 for (int j = 0; j < 4; ++j) { v0[j] = sigmoidf_(v0[j]); v1[j] = sigmoidf_(v1[j]); }
;                             }
;                             u32x4 w; w.x = cvt_pk_bf16(v0[0], v0[1]); w.y = cvt_pk_bf16(v0[2], v0[3]); w.z = cvt_pk_bf16(v1[0], v1[1]); w.w = cvt_pk_bf16(v1[2], v1[3]);
;                             *(u32x4*)(rowp + bj * 128) = w;
	v_fma_f32 v181, v179, s15, v188
	v_fma_f32 v166, v166, v164, v189
	v_fma_f32 v169, v169, v167, v189
	v_fma_f32 v172, v172, v170, v189
	v_fma_f32 v175, v175, v173, v189
	v_fma_f32 v178, v178, v176, v189
	v_fma_f32 v181, v181, v179, v189
	v_fma_f32 v166, v166, v164, v190
	v_fma_f32 v169, v169, v167, v190
	v_fma_f32 v172, v172, v170, v190
	v_fma_f32 v175, v175, v173, v190
	v_fma_f32 v178, v178, v176, v190
	v_fma_f32 v181, v181, v179, v190
	v_fma_f32 v166, v166, v164, v191
	v_fma_f32 v169, v169, v167, v191
	v_fma_f32 v172, v172, v170, v191
	v_fma_f32 v175, v175, v173, v191
	v_fma_f32 v178, v178, v176, v191
	v_fma_f32 v181, v181, v179, v191
	v_mul_f32_e32 v166, v166, v164
	v_mul_f32_e32 v169, v169, v167
	v_mul_f32_e32 v172, v172, v170
	v_mul_f32_e32 v175, v175, v173
	v_mul_f32_e32 v178, v178, v176
	v_mul_f32_e32 v181, v181, v179
	v_mul_f32_e32 v166, v166, v165
	v_mul_f32_e32 v169, v169, v168
	v_mul_f32_e32 v172, v172, v171
	v_mul_f32_e32 v175, v175, v174
	v_mul_f32_e32 v178, v178, v177
	v_mul_f32_e32 v181, v181, v180
	v_mul_f32_e32 v166, v156, v166
	v_mul_f32_e32 v169, v150, v169
	v_mul_f32_e32 v172, v157, v172
	v_mul_f32_e32 v175, v151, v175
	v_mul_f32_e32 v178, v154, v178
	v_mul_f32_e32 v181, v155, v181
	v_sub_f32_e32 v165, v156, v166
	v_sub_f32_e32 v168, v150, v169
	v_sub_f32_e32 v171, v157, v172
	v_sub_f32_e32 v174, v151, v175
	v_sub_f32_e32 v177, v154, v178
	v_sub_f32_e32 v180, v155, v181
	v_cmp_gt_f32_e64 s[100:101], 0, v156
	s_nop 1
	v_cndmask_b32_e64 v156, v165, v166, s[100:101]
	v_cmp_gt_f32_e64 s[100:101], 0, v150
	s_nop 1
	v_cndmask_b32_e64 v150, v168, v169, s[100:101]
	v_cmp_gt_f32_e64 s[100:101], 0, v157
	s_nop 1
	v_cndmask_b32_e64 v157, v171, v172, s[100:101]
	v_cmp_gt_f32_e64 s[100:101], 0, v151
	s_nop 1
	v_cndmask_b32_e64 v151, v174, v175, s[100:101]
	v_cmp_gt_f32_e64 s[100:101], 0, v154
	s_nop 1
	v_cndmask_b32_e64 v154, v177, v178, s[100:101]
	v_cmp_gt_f32_e64 s[100:101], 0, v155
	s_nop 1
	v_cndmask_b32_e64 v155, v180, v181, s[100:101]
	v_mov_b32_e32 v160, v154
	v_mov_b32_e32 v161, v155
	v_cvt_pk_bf16_f32 v154, v156, v157
	v_cvt_pk_bf16_f32 v155, v160, v161
	v_cvt_pk_bf16_f32 v156, v150, v151
	v_cvt_pk_bf16_f32 v157, v158, v159
	global_store_dwordx4 v[136:137], v[154:157], off offset:256
	v_lshl_add_u64 v[150:151], v[152:153], 0, v[146:147]
	v_pk_mul_f32 v[146:147], v[102:103], v[148:149] op_sel_hi:[1,0]
	v_pk_mul_f32 v[154:155], v[100:101], v[148:149] op_sel_hi:[1,0]
	v_pk_mul_f32 v[156:157], v[98:99], v[148:149] op_sel_hi:[1,0]
	v_pk_mul_f32 v[158:159], v[96:97], v[148:149] op_sel_hi:[1,0]
	v_and_b32_e32 v164, 0x7fffffff, v154
	v_and_b32_e32 v167, 0x7fffffff, v158
	v_and_b32_e32 v170, 0x7fffffff, v155
	v_and_b32_e32 v173, 0x7fffffff, v159
	v_and_b32_e32 v176, 0x7fffffff, v146
	v_and_b32_e32 v179, 0x7fffffff, v156
	v_and_b32_e32 v182, 0x7fffffff, v147
	v_and_b32_e32 v185, 0x7fffffff, v157
	v_mul_f32_e32 v165, v154, v154
	v_mul_f32_e32 v168, v158, v158
	v_mul_f32_e32 v171, v155, v155
	v_mul_f32_e32 v174, v159, v159
	v_mul_f32_e32 v177, v146, v146
	v_mul_f32_e32 v180, v156, v156
	v_mul_f32_e32 v183, v147, v147
	v_mul_f32_e32 v186, v157, v157
	v_fma_f32 v164, v164, s14, 1.0
	v_fma_f32 v167, v167, s14, 1.0
	v_fma_f32 v170, v170, s14, 1.0
	v_fma_f32 v173, v173, s14, 1.0
	v_fma_f32 v176, v176, s14, 1.0
	v_fma_f32 v179, v179, s14, 1.0
	v_fma_f32 v182, v182, s14, 1.0
	v_fma_f32 v185, v185, s14, 1.0
	v_mul_f32_e32 v165, s20, v165
	v_mul_f32_e32 v168, s20, v168
	v_mul_f32_e32 v171, s20, v171
	v_mul_f32_e32 v174, s20, v174
	v_mul_f32_e32 v177, s20, v177
	v_mul_f32_e32 v180, s20, v180
	v_mul_f32_e32 v183, s20, v183
	v_mul_f32_e32 v186, s20, v186
	v_rcp_f32_e32 v164, v164
	v_rcp_f32_e32 v167, v167
	v_rcp_f32_e32 v170, v170
	v_rcp_f32_e32 v173, v173
	v_rcp_f32_e32 v176, v176
	v_rcp_f32_e32 v179, v179
	v_rcp_f32_e32 v182, v182
	v_rcp_f32_e32 v185, v185
	s_nop 0
	v_exp_f32_e32 v165, v165
	v_exp_f32_e32 v168, v168
	v_exp_f32_e32 v171, v171
	v_exp_f32_e32 v174, v174
	v_exp_f32_e32 v177, v177
	v_exp_f32_e32 v180, v180
	v_exp_f32_e32 v183, v183
	v_exp_f32_e32 v186, v186
	s_nop 0
	v_fma_f32 v166, v164, s15, v188
	v_fma_f32 v169, v167, s15, v188
	v_fma_f32 v172, v170, s15, v188
	v_fma_f32 v175, v173, s15, v188
	v_fma_f32 v178, v176, s15, v188
	v_fma_f32 v181, v179, s15, v188
	v_fma_f32 v184, v182, s15, v188
	v_fma_f32 v187, v185, s15, v188
	v_fma_f32 v166, v166, v164, v189
	v_fma_f32 v169, v169, v167, v189
	v_fma_f32 v172, v172, v170, v189
	v_fma_f32 v175, v175, v173, v189
	v_fma_f32 v178, v178, v176, v189
	v_fma_f32 v181, v181, v179, v189
	v_fma_f32 v184, v184, v182, v189
	v_fma_f32 v187, v187, v185, v189
	v_fma_f32 v166, v166, v164, v190
	v_fma_f32 v169, v169, v167, v190
	v_fma_f32 v172, v172, v170, v190
	v_fma_f32 v175, v175, v173, v190
	v_fma_f32 v178, v178, v176, v190
	v_fma_f32 v181, v181, v179, v190
	v_fma_f32 v184, v184, v182, v190
	v_fma_f32 v187, v187, v185, v190
	v_fma_f32 v166, v166, v164, v191
	v_fma_f32 v169, v169, v167, v191
	v_fma_f32 v172, v172, v170, v191
	v_fma_f32 v175, v175, v173, v191
	v_fma_f32 v178, v178, v176, v191
	v_fma_f32 v181, v181, v179, v191
	v_fma_f32 v184, v184, v182, v191
	v_fma_f32 v187, v187, v185, v191
	v_mul_f32_e32 v166, v166, v164
	v_mul_f32_e32 v169, v169, v167
	v_mul_f32_e32 v172, v172, v170
	v_mul_f32_e32 v175, v175, v173
	v_mul_f32_e32 v178, v178, v176
	v_mul_f32_e32 v181, v181, v179
	v_mul_f32_e32 v184, v184, v182
	v_mul_f32_e32 v187, v187, v185
	v_mul_f32_e32 v166, v166, v165
	v_mul_f32_e32 v169, v169, v168
	v_mul_f32_e32 v172, v172, v171
	v_mul_f32_e32 v175, v175, v174
	v_mul_f32_e32 v178, v178, v177
	v_mul_f32_e32 v181, v181, v180
	v_mul_f32_e32 v184, v184, v183
	v_mul_f32_e32 v187, v187, v186
; __device__ __forceinline__ unsigned cvt_pk_bf16(float lo, float hi) { const f32x2 v = {lo, hi}; const bf16v2_t b = __builtin_convertvector(v, bf16v2_t); return __builtin_bit_cast(unsigned, b); }
; __device__ __forceinline__ float sigmoidf_(float x) { return __builtin_amdgcn_rcpf(1.0f + __builtin_amdgcn_exp2f(x * -1.44269504089f)); }
; __device__ __forceinline__ float siluf_(float x) { return x * __builtin_amdgcn_rcpf(1.0f + __builtin_amdgcn_exp2f(x * -1.44269504089f)); }
; __device__ __forceinline__ f32x2 gelu_pk(f32x2 v) {
;     const f32x2 av = __builtin_elementwise_abs(v), d = av * 0.2316418882f + 1.0f;
;     f32x2 t; t.x = __builtin_amdgcn_rcpf(d.x); t.y = __builtin_amdgcn_rcpf(d.y);
;     f32x2 q = t * 0.5307027145f + (-0.7265760135f); q = q * t + 0.7107068705f; q = q * t + (-0.142248368f); q = q * t + 0.127414796f; q = q * t;
;     const f32x2 s = (v * v) * (-0.72134752044f);
;     f32x2 e; e.x = __builtin_amdgcn_exp2f(s.x); e.y = __builtin_amdgcn_exp2f(s.y);
;     const f32x2 m = v * (q * e), r = v - m;
;     f32x2 o; o.x = v.x < 0.f ? m.x : r.x; o.y = v.y < 0.f ? m.y : r.y; return o;
;     __device__ __forceinline__ void epi_proj(const f32x4 (&acc)[2][2][4][2], const pg8::Unit& u, int wr, int wc, int fr, int fq) const {
;     ...
;                             f32x4 v0 = acc[ai][bj][m][0] * rstd, v1 = acc[ai][bj][m][1] * rstd;
;                             if (slot < 2) {
;                                 f32x2 a = gelu_pk((f32x2){v0[0], v0[1]}), b = gelu_pk((f32x2){v0[2], v0[3]}), c = gelu_pk((f32x2){v1[0], v1[1]}), d = gelu_pk((f32x2){v1[2], v1[3]});
;                                 v0 = (f32x4){a.x, a.y, b.x, b.y}; v1 = (f32x4){c.x, c.y, d.x, d.y};
;                             } else if (slot == 5) {
; #pragma unroll
;                                 for (int j = 0; j < 4; ++j) { v0[j] = siluf_(v0[j]); v1[j] = siluf_(v1[j]); }
;                             } else if (slot >= 6) {
; #pragma unroll
;                                 for (int j = 0; j < 4; ++j) { v0[j] = sigmoidf_(v0[j]); v1[j] = sigmoidf_(v1[j]); }
;                             }
;                             u32x4 w; w.x = cvt_pk_bf16(v0[0], v0[1]); w.y = cvt_pk_bf16(v0[2], v0[3]); w.z = cvt_pk_bf16(v1[0], v1[1]); w.w = cvt_pk_bf16(v1[2], v1[3]);
;                             *(u32x4*)(rowp + bj * 128) = w;
	v_mul_f32_e32 v166, v154, v166
	v_mul_f32_e32 v169, v158, v169
	v_mul_f32_e32 v172, v155, v172
	v_mul_f32_e32 v175, v159, v175
	v_mul_f32_e32 v178, v146, v178
	v_mul_f32_e32 v181, v156, v181
	v_mul_f32_e32 v184, v147, v184
	v_mul_f32_e32 v187, v157, v187
	v_sub_f32_e32 v165, v154, v166
	v_sub_f32_e32 v168, v158, v169
	v_sub_f32_e32 v171, v155, v172
	v_sub_f32_e32 v174, v159, v175
	v_sub_f32_e32 v177, v146, v178
	v_sub_f32_e32 v180, v156, v181
	v_sub_f32_e32 v183, v147, v184
	v_sub_f32_e32 v186, v157, v187
	v_cmp_gt_f32_e64 s[100:101], 0, v154
	s_nop 1
	v_cndmask_b32_e64 v154, v165, v166, s[100:101]
	v_cmp_gt_f32_e64 s[100:101], 0, v158
	s_nop 1
	v_cndmask_b32_e64 v158, v168, v169, s[100:101]
	v_cmp_gt_f32_e64 s[100:101], 0, v155
	s_nop 1
	v_cndmask_b32_e64 v155, v171, v172, s[100:101]
	v_cmp_gt_f32_e64 s[100:101], 0, v159
	s_nop 1
	v_cndmask_b32_e64 v159, v174, v175, s[100:101]
	v_cmp_gt_f32_e64 s[100:101], 0, v146
	s_nop 1
	v_cndmask_b32_e64 v146, v177, v178, s[100:101]
	v_cmp_gt_f32_e64 s[100:101], 0, v156
	s_nop 1
	v_cndmask_b32_e64 v156, v180, v181, s[100:101]
	v_cmp_gt_f32_e64 s[100:101], 0, v147
	s_nop 1
	v_cndmask_b32_e64 v147, v183, v184, s[100:101]
	v_cmp_gt_f32_e64 s[100:101], 0, v157
	s_nop 1
	v_cndmask_b32_e64 v157, v186, v187, s[100:101]
	v_mov_b32_e32 v160, v156
	v_mov_b32_e32 v161, v157
	v_cvt_pk_bf16_f32 v154, v154, v155
	v_cvt_pk_bf16_f32 v155, v146, v147
	v_cvt_pk_bf16_f32 v156, v158, v159
	v_cvt_pk_bf16_f32 v157, v160, v161
	global_store_dwordx4 v[150:151], v[154:157], off
	v_pk_mul_f32 v[146:147], v[110:111], v[148:149] op_sel_hi:[1,0]
	v_rsq_f32_e32 v128, v128
	v_pk_mul_f32 v[154:155], v[108:109], v[148:149] op_sel_hi:[1,0]
	v_pk_mul_f32 v[156:157], v[106:107], v[148:149] op_sel_hi:[1,0]
	v_pk_mul_f32 v[148:149], v[104:105], v[148:149] op_sel_hi:[1,0]
	v_and_b32_e32 v164, 0x7fffffff, v154
	v_and_b32_e32 v167, 0x7fffffff, v148
	v_and_b32_e32 v170, 0x7fffffff, v155
	v_and_b32_e32 v173, 0x7fffffff, v149
	v_and_b32_e32 v176, 0x7fffffff, v146
	v_and_b32_e32 v179, 0x7fffffff, v156
	v_and_b32_e32 v182, 0x7fffffff, v147
	v_and_b32_e32 v185, 0x7fffffff, v157
	v_mul_f32_e32 v165, v154, v154
	v_mul_f32_e32 v168, v148, v148
	v_mul_f32_e32 v171, v155, v155
	v_mul_f32_e32 v174, v149, v149
	v_mul_f32_e32 v177, v146, v146
	v_mul_f32_e32 v180, v156, v156
	v_mul_f32_e32 v183, v147, v147
	v_mul_f32_e32 v186, v157, v157
	v_fma_f32 v164, v164, s14, 1.0
	v_fma_f32 v167, v167, s14, 1.0
	v_fma_f32 v170, v170, s14, 1.0
	v_fma_f32 v173, v173, s14, 1.0
	v_fma_f32 v176, v176, s14, 1.0
	v_fma_f32 v179, v179, s14, 1.0
	v_fma_f32 v182, v182, s14, 1.0
	v_fma_f32 v185, v185, s14, 1.0
	v_mul_f32_e32 v165, s20, v165
	v_mul_f32_e32 v168, s20, v168
	v_mul_f32_e32 v171, s20, v171
	v_mul_f32_e32 v174, s20, v174
	v_mul_f32_e32 v177, s20, v177
	v_mul_f32_e32 v180, s20, v180
	v_mul_f32_e32 v183, s20, v183
	v_mul_f32_e32 v186, s20, v186
	v_rcp_f32_e32 v164, v164
	v_rcp_f32_e32 v167, v167
	v_rcp_f32_e32 v170, v170
	v_rcp_f32_e32 v173, v173
	v_rcp_f32_e32 v176, v176
	v_rcp_f32_e32 v179, v179
	v_rcp_f32_e32 v182, v182
	v_rcp_f32_e32 v185, v185
	s_nop 0
	v_exp_f32_e32 v165, v165
	v_exp_f32_e32 v168, v168
	v_exp_f32_e32 v171, v171
	v_exp_f32_e32 v174, v174
	v_exp_f32_e32 v177, v177
	v_exp_f32_e32 v180, v180
	v_exp_f32_e32 v183, v183
	v_exp_f32_e32 v186, v186
	s_nop 0
	v_fma_f32 v166, v164, s15, v188
	v_fma_f32 v169, v167, s15, v188
	v_fma_f32 v172, v170, s15, v188
	v_fma_f32 v175, v173, s15, v188
	v_fma_f32 v178, v176, s15, v188
	v_fma_f32 v181, v179, s15, v188
	v_fma_f32 v184, v182, s15, v188
	v_fma_f32 v187, v185, s15, v188
	v_fma_f32 v166, v166, v164, v189
	v_fma_f32 v169, v169, v167, v189
	v_fma_f32 v172, v172, v170, v189
	v_fma_f32 v175, v175, v173, v189
	v_fma_f32 v178, v178, v176, v189
	v_fma_f32 v181, v181, v179, v189
	v_fma_f32 v184, v184, v182, v189
	v_fma_f32 v187, v187, v185, v189
	v_fma_f32 v166, v166, v164, v190
	v_fma_f32 v169, v169, v167, v190
	v_fma_f32 v172, v172, v170, v190
	v_fma_f32 v175, v175, v173, v190
	v_fma_f32 v178, v178, v176, v190
	v_fma_f32 v181, v181, v179, v190
	v_fma_f32 v184, v184, v182, v190
	v_fma_f32 v187, v187, v185, v190
	v_fma_f32 v166, v166, v164, v191
	v_fma_f32 v169, v169, v167, v191
	v_fma_f32 v172, v172, v170, v191
	v_fma_f32 v175, v175, v173, v191
	v_fma_f32 v178, v178, v176, v191
	v_fma_f32 v181, v181, v179, v191
	v_fma_f32 v184, v184, v182, v191
	v_fma_f32 v187, v187, v185, v191
	v_mul_f32_e32 v166, v166, v164
	v_mul_f32_e32 v169, v169, v167
	v_mul_f32_e32 v172, v172, v170
	v_mul_f32_e32 v175, v175, v173
	v_mul_f32_e32 v178, v178, v176
	v_mul_f32_e32 v181, v181, v179
	v_mul_f32_e32 v184, v184, v182
	v_mul_f32_e32 v187, v187, v185
	v_mul_f32_e32 v166, v166, v165
	v_mul_f32_e32 v169, v169, v168
	v_mul_f32_e32 v172, v172, v171
	v_mul_f32_e32 v175, v175, v174
	v_mul_f32_e32 v178, v178, v177
	v_mul_f32_e32 v181, v181, v180
	v_mul_f32_e32 v184, v184, v183
	v_mul_f32_e32 v187, v187, v186
	v_mul_f32_e32 v166, v154, v166
	v_mul_f32_e32 v169, v148, v169
	v_mul_f32_e32 v172, v155, v172
	v_mul_f32_e32 v175, v149, v175
	v_mul_f32_e32 v178, v146, v178
	v_mul_f32_e32 v181, v156, v181
	v_mul_f32_e32 v184, v147, v184
	v_mul_f32_e32 v187, v157, v187
	v_sub_f32_e32 v165, v154, v166
	v_sub_f32_e32 v168, v148, v169
	v_sub_f32_e32 v171, v155, v172
	v_sub_f32_e32 v174, v149, v175
	v_sub_f32_e32 v177, v146, v178
	v_sub_f32_e32 v180, v156, v181
	v_sub_f32_e32 v183, v147, v184
	v_sub_f32_e32 v186, v157, v187
	v_cmp_gt_f32_e64 s[100:101], 0, v154
	s_nop 1
	v_cndmask_b32_e64 v154, v165, v166, s[100:101]
	v_cmp_gt_f32_e64 s[100:101], 0, v148
	s_nop 1
	v_cndmask_b32_e64 v148, v168, v169, s[100:101]
	v_cmp_gt_f32_e64 s[100:101], 0, v155
	s_nop 1
; __device__ __forceinline__ unsigned cvt_pk_bf16(float lo, float hi) { const f32x2 v = {lo, hi}; const bf16v2_t b = __builtin_convertvector(v, bf16v2_t); return __builtin_bit_cast(unsigned, b); }
; __device__ __forceinline__ float sigmoidf_(float x) { return __builtin_amdgcn_rcpf(1.0f + __builtin_amdgcn_exp2f(x * -1.44269504089f)); }
; __device__ __forceinline__ float siluf_(float x) { return x * __builtin_amdgcn_rcpf(1.0f + __builtin_amdgcn_exp2f(x * -1.44269504089f)); }
; __device__ __forceinline__ f32x2 gelu_pk(f32x2 v) {
;     const f32x2 av = __builtin_elementwise_abs(v), d = av * 0.2316418882f + 1.0f;
;     f32x2 t; t.x = __builtin_amdgcn_rcpf(d.x); t.y = __builtin_amdgcn_rcpf(d.y);
;     f32x2 q = t * 0.5307027145f + (-0.7265760135f); q = q * t + 0.7107068705f; q = q * t + (-0.142248368f); q = q * t + 0.127414796f; q = q * t;
;     const f32x2 s = (v * v) * (-0.72134752044f);
;     f32x2 e; e.x = __builtin_amdgcn_exp2f(s.x); e.y = __builtin_amdgcn_exp2f(s.y);
;     const f32x2 m = v * (q * e), r = v - m;
;     f32x2 o; o.x = v.x < 0.f ? m.x : r.x; o.y = v.y < 0.f ? m.y : r.y; return o;
;     __device__ __forceinline__ void epi_proj(const f32x4 (&acc)[2][2][4][2], const pg8::Unit& u, int wr, int wc, int fr, int fq) const {
;     ...
;                             f32x4 v0 = acc[ai][bj][m][0] * rstd, v1 = acc[ai][bj][m][1] * rstd;
;                             if (slot < 2) {
;                                 f32x2 a = gelu_pk((f32x2){v0[0], v0[1]}), b = gelu_pk((f32x2){v0[2], v0[3]}), c = gelu_pk((f32x2){v1[0], v1[1]}), d = gelu_pk((f32x2){v1[2], v1[3]});
;                                 v0 = (f32x4){a.x, a.y, b.x, b.y}; v1 = (f32x4){c.x, c.y, d.x, d.y};
;                             } else if (slot == 5) {
; #pragma unroll
;                                 for (int j = 0; j < 4; ++j) { v0[j] = siluf_(v0[j]); v1[j] = siluf_(v1[j]); }
;                             } else if (slot >= 6) {
; #pragma unroll
;                                 for (int j = 0; j < 4; ++j) { v0[j] = sigmoidf_(v0[j]); v1[j] = sigmoidf_(v1[j]); }
;                             }
;                             u32x4 w; w.x = cvt_pk_bf16(v0[0], v0[1]); w.y = cvt_pk_bf16(v0[2], v0[3]); w.z = cvt_pk_bf16(v1[0], v1[1]); w.w = cvt_pk_bf16(v1[2], v1[3]);
;                             *(u32x4*)(rowp + bj * 128) = w;
	v_cndmask_b32_e64 v155, v171, v172, s[100:101]
	v_cmp_gt_f32_e64 s[100:101], 0, v149
	s_nop 1
	v_cndmask_b32_e64 v149, v174, v175, s[100:101]
	v_cmp_gt_f32_e64 s[100:101], 0, v146
	s_nop 1
	v_cndmask_b32_e64 v146, v177, v178, s[100:101]
	v_cmp_gt_f32_e64 s[100:101], 0, v156
	s_nop 1
	v_cndmask_b32_e64 v156, v180, v181, s[100:101]
	v_cmp_gt_f32_e64 s[100:101], 0, v147
	s_nop 1
	v_cndmask_b32_e64 v147, v183, v184, s[100:101]
	v_cmp_gt_f32_e64 s[100:101], 0, v157
	s_nop 1
	v_cndmask_b32_e64 v157, v186, v187, s[100:101]
	v_mov_b32_e32 v158, v146
	v_mov_b32_e32 v159, v147
	v_cvt_pk_bf16_f32 v146, v154, v155
	v_cvt_pk_bf16_f32 v147, v158, v159
	v_cvt_pk_bf16_f32 v148, v148, v149
	v_cvt_pk_bf16_f32 v149, v156, v157
	global_store_dwordx4 v[150:151], v[146:149], off offset:256
	v_lshl_add_u64 v[150:151], v[152:153], 0, v[142:143]
	v_pk_mul_f32 v[142:143], v[86:87], v[144:145] op_sel_hi:[1,0]
	v_pk_mul_f32 v[146:147], v[84:85], v[144:145] op_sel_hi:[1,0]
	v_pk_mul_f32 v[148:149], v[82:83], v[144:145] op_sel_hi:[1,0]
	v_pk_mul_f32 v[154:155], v[80:81], v[144:145] op_sel_hi:[1,0]
	v_and_b32_e32 v164, 0x7fffffff, v146
	v_and_b32_e32 v167, 0x7fffffff, v154
	v_and_b32_e32 v170, 0x7fffffff, v147
	v_and_b32_e32 v173, 0x7fffffff, v155
	v_and_b32_e32 v176, 0x7fffffff, v142
	v_and_b32_e32 v179, 0x7fffffff, v148
	v_and_b32_e32 v182, 0x7fffffff, v143
	v_and_b32_e32 v185, 0x7fffffff, v149
	v_mul_f32_e32 v165, v146, v146
	v_mul_f32_e32 v168, v154, v154
	v_mul_f32_e32 v171, v147, v147
	v_mul_f32_e32 v174, v155, v155
	v_mul_f32_e32 v177, v142, v142
	v_mul_f32_e32 v180, v148, v148
	v_mul_f32_e32 v183, v143, v143
	v_mul_f32_e32 v186, v149, v149
	v_fma_f32 v164, v164, s14, 1.0
	v_fma_f32 v167, v167, s14, 1.0
	v_fma_f32 v170, v170, s14, 1.0
	v_fma_f32 v173, v173, s14, 1.0
	v_fma_f32 v176, v176, s14, 1.0
	v_fma_f32 v179, v179, s14, 1.0
	v_fma_f32 v182, v182, s14, 1.0
	v_fma_f32 v185, v185, s14, 1.0
	v_mul_f32_e32 v165, s20, v165
	v_mul_f32_e32 v168, s20, v168
	v_mul_f32_e32 v171, s20, v171
	v_mul_f32_e32 v174, s20, v174
	v_mul_f32_e32 v177, s20, v177
	v_mul_f32_e32 v180, s20, v180
	v_mul_f32_e32 v183, s20, v183
	v_mul_f32_e32 v186, s20, v186
	v_rcp_f32_e32 v164, v164
	v_rcp_f32_e32 v167, v167
	v_rcp_f32_e32 v170, v170
	v_rcp_f32_e32 v173, v173
	v_rcp_f32_e32 v176, v176
	v_rcp_f32_e32 v179, v179
	v_rcp_f32_e32 v182, v182
	v_rcp_f32_e32 v185, v185
	s_nop 0
	v_exp_f32_e32 v165, v165
	v_exp_f32_e32 v168, v168
	v_exp_f32_e32 v171, v171
	v_exp_f32_e32 v174, v174
	v_exp_f32_e32 v177, v177
	v_exp_f32_e32 v180, v180
	v_exp_f32_e32 v183, v183
	v_exp_f32_e32 v186, v186
	s_nop 0
	v_fma_f32 v166, v164, s15, v188
	v_fma_f32 v169, v167, s15, v188
	v_fma_f32 v172, v170, s15, v188
	v_fma_f32 v175, v173, s15, v188
	v_fma_f32 v178, v176, s15, v188
	v_fma_f32 v181, v179, s15, v188
	v_fma_f32 v184, v182, s15, v188
	v_fma_f32 v187, v185, s15, v188
	v_fma_f32 v166, v166, v164, v189
	v_fma_f32 v169, v169, v167, v189
	v_fma_f32 v172, v172, v170, v189
	v_fma_f32 v175, v175, v173, v189
	v_fma_f32 v178, v178, v176, v189
	v_fma_f32 v181, v181, v179, v189
	v_fma_f32 v184, v184, v182, v189
	v_fma_f32 v187, v187, v185, v189
	v_fma_f32 v166, v166, v164, v190
	v_fma_f32 v169, v169, v167, v190
	v_fma_f32 v172, v172, v170, v190
	v_fma_f32 v175, v175, v173, v190
	v_fma_f32 v178, v178, v176, v190
	v_fma_f32 v181, v181, v179, v190
	v_fma_f32 v184, v184, v182, v190
	v_fma_f32 v187, v187, v185, v190
	v_fma_f32 v166, v166, v164, v191
	v_fma_f32 v169, v169, v167, v191
	v_fma_f32 v172, v172, v170, v191
	v_fma_f32 v175, v175, v173, v191
	v_fma_f32 v178, v178, v176, v191
	v_fma_f32 v181, v181, v179, v191
	v_fma_f32 v184, v184, v182, v191
	v_fma_f32 v187, v187, v185, v191
	v_mul_f32_e32 v166, v166, v164
	v_mul_f32_e32 v169, v169, v167
	v_mul_f32_e32 v172, v172, v170
	v_mul_f32_e32 v175, v175, v173
	v_mul_f32_e32 v178, v178, v176
	v_mul_f32_e32 v181, v181, v179
	v_mul_f32_e32 v184, v184, v182
	v_mul_f32_e32 v187, v187, v185
	v_mul_f32_e32 v166, v166, v165
	v_mul_f32_e32 v169, v169, v168
	v_mul_f32_e32 v172, v172, v171
	v_mul_f32_e32 v175, v175, v174
	v_mul_f32_e32 v178, v178, v177
	v_mul_f32_e32 v181, v181, v180
	v_mul_f32_e32 v184, v184, v183
	v_mul_f32_e32 v187, v187, v186
	v_mul_f32_e32 v166, v146, v166
	v_mul_f32_e32 v169, v154, v169
	v_mul_f32_e32 v172, v147, v172
	v_mul_f32_e32 v175, v155, v175
	v_mul_f32_e32 v178, v142, v178
	v_mul_f32_e32 v181, v148, v181
	v_mul_f32_e32 v184, v143, v184
	v_mul_f32_e32 v187, v149, v187
	v_sub_f32_e32 v165, v146, v166
	v_sub_f32_e32 v168, v154, v169
	v_sub_f32_e32 v171, v147, v172
	v_sub_f32_e32 v174, v155, v175
	v_sub_f32_e32 v177, v142, v178
	v_sub_f32_e32 v180, v148, v181
	v_sub_f32_e32 v183, v143, v184
	v_sub_f32_e32 v186, v149, v187
	v_cmp_gt_f32_e64 s[100:101], 0, v146
	s_nop 1
	v_cndmask_b32_e64 v146, v165, v166, s[100:101]
	v_cmp_gt_f32_e64 s[100:101], 0, v154
	s_nop 1
	v_cndmask_b32_e64 v154, v168, v169, s[100:101]
	v_cmp_gt_f32_e64 s[100:101], 0, v147
	s_nop 1
	v_cndmask_b32_e64 v147, v171, v172, s[100:101]
	v_cmp_gt_f32_e64 s[100:101], 0, v155
	s_nop 1
	v_cndmask_b32_e64 v155, v174, v175, s[100:101]
	v_cmp_gt_f32_e64 s[100:101], 0, v142
	s_nop 1
	v_cndmask_b32_e64 v142, v177, v178, s[100:101]
	v_cmp_gt_f32_e64 s[100:101], 0, v148
	s_nop 1
	v_cndmask_b32_e64 v148, v180, v181, s[100:101]
	v_cmp_gt_f32_e64 s[100:101], 0, v143
	s_nop 1
	v_cndmask_b32_e64 v143, v183, v184, s[100:101]
	v_cmp_gt_f32_e64 s[100:101], 0, v149
	s_nop 1
	v_cndmask_b32_e64 v149, v186, v187, s[100:101]
	v_mov_b32_e32 v156, v148
	v_mov_b32_e32 v157, v149
	v_cvt_pk_bf16_f32 v146, v146, v147
	v_cvt_pk_bf16_f32 v147, v142, v143
	v_cvt_pk_bf16_f32 v148, v154, v155
	v_cvt_pk_bf16_f32 v149, v156, v157
; __device__ __forceinline__ unsigned cvt_pk_bf16(float lo, float hi) { const f32x2 v = {lo, hi}; const bf16v2_t b = __builtin_convertvector(v, bf16v2_t); return __builtin_bit_cast(unsigned, b); }
; __device__ __forceinline__ float sigmoidf_(float x) { return __builtin_amdgcn_rcpf(1.0f + __builtin_amdgcn_exp2f(x * -1.44269504089f)); }
; __device__ __forceinline__ float siluf_(float x) { return x * __builtin_amdgcn_rcpf(1.0f + __builtin_amdgcn_exp2f(x * -1.44269504089f)); }
; __device__ __forceinline__ f32x2 gelu_pk(f32x2 v) {
;     const f32x2 av = __builtin_elementwise_abs(v), d = av * 0.2316418882f + 1.0f;
;     f32x2 t; t.x = __builtin_amdgcn_rcpf(d.x); t.y = __builtin_amdgcn_rcpf(d.y);
;     f32x2 q = t * 0.5307027145f + (-0.7265760135f); q = q * t + 0.7107068705f; q = q * t + (-0.142248368f); q = q * t + 0.127414796f; q = q * t;
;     const f32x2 s = (v * v) * (-0.72134752044f);
;     f32x2 e; e.x = __builtin_amdgcn_exp2f(s.x); e.y = __builtin_amdgcn_exp2f(s.y);
;     const f32x2 m = v * (q * e), r = v - m;
;     f32x2 o; o.x = v.x < 0.f ? m.x : r.x; o.y = v.y < 0.f ? m.y : r.y; return o;
;     __device__ __forceinline__ void epi_proj(const f32x4 (&acc)[2][2][4][2], const pg8::Unit& u, int wr, int wc, int fr, int fq) const {
;     ...
;                             f32x4 v0 = acc[ai][bj][m][0] * rstd, v1 = acc[ai][bj][m][1] * rstd;
;                             if (slot < 2) {
;                                 f32x2 a = gelu_pk((f32x2){v0[0], v0[1]}), b = gelu_pk((f32x2){v0[2], v0[3]}), c = gelu_pk((f32x2){v1[0], v1[1]}), d = gelu_pk((f32x2){v1[2], v1[3]});
;                                 v0 = (f32x4){a.x, a.y, b.x, b.y}; v1 = (f32x4){c.x, c.y, d.x, d.y};
;                             } else if (slot == 5) {
; #pragma unroll
;                                 for (int j = 0; j < 4; ++j) { v0[j] = siluf_(v0[j]); v1[j] = siluf_(v1[j]); }
;                             } else if (slot >= 6) {
; #pragma unroll
;                                 for (int j = 0; j < 4; ++j) { v0[j] = sigmoidf_(v0[j]); v1[j] = sigmoidf_(v1[j]); }
;                             }
;                             u32x4 w; w.x = cvt_pk_bf16(v0[0], v0[1]); w.y = cvt_pk_bf16(v0[2], v0[3]); w.z = cvt_pk_bf16(v1[0], v1[1]); w.w = cvt_pk_bf16(v1[2], v1[3]);
;                             *(u32x4*)(rowp + bj * 128) = w;
	global_store_dwordx4 v[150:151], v[146:149], off
	v_pk_mul_f32 v[142:143], v[94:95], v[144:145] op_sel_hi:[1,0]
	s_mov_b64 s[0:1], 0x40000
	v_pk_mul_f32 v[146:147], v[92:93], v[144:145] op_sel_hi:[1,0]
	v_pk_mul_f32 v[148:149], v[90:91], v[144:145] op_sel_hi:[1,0]
	v_pk_mul_f32 v[144:145], v[88:89], v[144:145] op_sel_hi:[1,0]
	v_and_b32_e32 v164, 0x7fffffff, v146
	v_and_b32_e32 v167, 0x7fffffff, v144
	v_and_b32_e32 v170, 0x7fffffff, v147
	v_and_b32_e32 v173, 0x7fffffff, v145
	v_and_b32_e32 v176, 0x7fffffff, v142
	v_and_b32_e32 v179, 0x7fffffff, v148
	v_and_b32_e32 v182, 0x7fffffff, v143
	v_and_b32_e32 v185, 0x7fffffff, v149
	v_mul_f32_e32 v165, v146, v146
	v_mul_f32_e32 v168, v144, v144
	v_mul_f32_e32 v171, v147, v147
	v_mul_f32_e32 v174, v145, v145
	v_mul_f32_e32 v177, v142, v142
	v_mul_f32_e32 v180, v148, v148
	v_mul_f32_e32 v183, v143, v143
	v_mul_f32_e32 v186, v149, v149
	v_fma_f32 v164, v164, s14, 1.0
	v_fma_f32 v167, v167, s14, 1.0
	v_fma_f32 v170, v170, s14, 1.0
	v_fma_f32 v173, v173, s14, 1.0
	v_fma_f32 v176, v176, s14, 1.0
	v_fma_f32 v179, v179, s14, 1.0
	v_fma_f32 v182, v182, s14, 1.0
	v_fma_f32 v185, v185, s14, 1.0
	v_mul_f32_e32 v165, s20, v165
	v_mul_f32_e32 v168, s20, v168
	v_mul_f32_e32 v171, s20, v171
	v_mul_f32_e32 v174, s20, v174
	v_mul_f32_e32 v177, s20, v177
	v_mul_f32_e32 v180, s20, v180
	v_mul_f32_e32 v183, s20, v183
	v_mul_f32_e32 v186, s20, v186
	v_rcp_f32_e32 v164, v164
	v_rcp_f32_e32 v167, v167
	v_rcp_f32_e32 v170, v170
	v_rcp_f32_e32 v173, v173
	v_rcp_f32_e32 v176, v176
	v_rcp_f32_e32 v179, v179
	v_rcp_f32_e32 v182, v182
	v_rcp_f32_e32 v185, v185
	s_nop 0
	v_exp_f32_e32 v165, v165
	v_exp_f32_e32 v168, v168
	v_exp_f32_e32 v171, v171
	v_exp_f32_e32 v174, v174
	v_exp_f32_e32 v177, v177
	v_exp_f32_e32 v180, v180
	v_exp_f32_e32 v183, v183
	v_exp_f32_e32 v186, v186
	s_nop 0
	v_fma_f32 v166, v164, s15, v188
	v_fma_f32 v169, v167, s15, v188
	v_fma_f32 v172, v170, s15, v188
	v_fma_f32 v175, v173, s15, v188
	v_fma_f32 v178, v176, s15, v188
	v_fma_f32 v181, v179, s15, v188
	v_fma_f32 v184, v182, s15, v188
	v_fma_f32 v187, v185, s15, v188
	v_fma_f32 v166, v166, v164, v189
	v_fma_f32 v169, v169, v167, v189
	v_fma_f32 v172, v172, v170, v189
	v_fma_f32 v175, v175, v173, v189
	v_fma_f32 v178, v178, v176, v189
	v_fma_f32 v181, v181, v179, v189
	v_fma_f32 v184, v184, v182, v189
	v_fma_f32 v187, v187, v185, v189
	v_fma_f32 v166, v166, v164, v190
	v_fma_f32 v169, v169, v167, v190
	v_fma_f32 v172, v172, v170, v190
	v_fma_f32 v175, v175, v173, v190
	v_fma_f32 v178, v178, v176, v190
	v_fma_f32 v181, v181, v179, v190
	v_fma_f32 v184, v184, v182, v190
	v_fma_f32 v187, v187, v185, v190
	v_fma_f32 v166, v166, v164, v191
	v_fma_f32 v169, v169, v167, v191
	v_fma_f32 v172, v172, v170, v191
	v_fma_f32 v175, v175, v173, v191
	v_fma_f32 v178, v178, v176, v191
	v_fma_f32 v181, v181, v179, v191
	v_fma_f32 v184, v184, v182, v191
	v_fma_f32 v187, v187, v185, v191
	v_mul_f32_e32 v166, v166, v164
	v_mul_f32_e32 v169, v169, v167
	v_mul_f32_e32 v172, v172, v170
	v_mul_f32_e32 v175, v175, v173
	v_mul_f32_e32 v178, v178, v176
	v_mul_f32_e32 v181, v181, v179
	v_mul_f32_e32 v184, v184, v182
	v_mul_f32_e32 v187, v187, v185
	v_mul_f32_e32 v166, v166, v165
	v_mul_f32_e32 v169, v169, v168
	v_mul_f32_e32 v172, v172, v171
	v_mul_f32_e32 v175, v175, v174
	v_mul_f32_e32 v178, v178, v177
	v_mul_f32_e32 v181, v181, v180
	v_mul_f32_e32 v184, v184, v183
	v_mul_f32_e32 v187, v187, v186
	v_mul_f32_e32 v166, v146, v166
	v_mul_f32_e32 v169, v144, v169
	v_mul_f32_e32 v172, v147, v172
	v_mul_f32_e32 v175, v145, v175
	v_mul_f32_e32 v178, v142, v178
	v_mul_f32_e32 v181, v148, v181
	v_mul_f32_e32 v184, v143, v184
	v_mul_f32_e32 v187, v149, v187
	v_sub_f32_e32 v165, v146, v166
	v_sub_f32_e32 v168, v144, v169
	v_sub_f32_e32 v171, v147, v172
	v_sub_f32_e32 v174, v145, v175
	v_sub_f32_e32 v177, v142, v178
	v_sub_f32_e32 v180, v148, v181
	v_sub_f32_e32 v183, v143, v184
	v_sub_f32_e32 v186, v149, v187
	v_cmp_gt_f32_e64 s[100:101], 0, v146
	s_nop 1
	v_cndmask_b32_e64 v146, v165, v166, s[100:101]
	v_cmp_gt_f32_e64 s[100:101], 0, v144
	s_nop 1
	v_cndmask_b32_e64 v144, v168, v169, s[100:101]
	v_cmp_gt_f32_e64 s[100:101], 0, v147
	s_nop 1
	v_cndmask_b32_e64 v147, v171, v172, s[100:101]
	v_cmp_gt_f32_e64 s[100:101], 0, v145
	s_nop 1
	v_cndmask_b32_e64 v145, v174, v175, s[100:101]
	v_cmp_gt_f32_e64 s[100:101], 0, v142
	s_nop 1
	v_cndmask_b32_e64 v142, v177, v178, s[100:101]
	v_cmp_gt_f32_e64 s[100:101], 0, v148
	s_nop 1
	v_cndmask_b32_e64 v148, v180, v181, s[100:101]
	v_cmp_gt_f32_e64 s[100:101], 0, v143
	s_nop 1
	v_cndmask_b32_e64 v143, v183, v184, s[100:101]
	v_cmp_gt_f32_e64 s[100:101], 0, v149
	s_nop 1
	v_cndmask_b32_e64 v149, v186, v187, s[100:101]
	v_mov_b32_e32 v154, v142
	v_mov_b32_e32 v155, v143
	v_cvt_pk_bf16_f32 v142, v146, v147
	v_cvt_pk_bf16_f32 v143, v154, v155
	v_cvt_pk_bf16_f32 v144, v144, v145
	v_cvt_pk_bf16_f32 v145, v148, v149
	global_store_dwordx4 v[150:151], v[142:145], off offset:256
	v_pk_mul_f32 v[146:147], v[66:67], v[138:139] op_sel_hi:[1,0]
	v_pk_mul_f32 v[148:149], v[64:65], v[138:139] op_sel_hi:[1,0]
	v_lshl_add_u64 v[144:145], v[152:153], 0, v[140:141]
	v_pk_mul_f32 v[140:141], v[70:71], v[138:139] op_sel_hi:[1,0]
	v_pk_mul_f32 v[142:143], v[68:69], v[138:139] op_sel_hi:[1,0]
	v_and_b32_e32 v164, 0x7fffffff, v148
	v_and_b32_e32 v167, 0x7fffffff, v142
	v_and_b32_e32 v170, 0x7fffffff, v143
	v_and_b32_e32 v173, 0x7fffffff, v149
	v_and_b32_e32 v176, 0x7fffffff, v140
	v_and_b32_e32 v179, 0x7fffffff, v146
	v_and_b32_e32 v182, 0x7fffffff, v141
	v_and_b32_e32 v185, 0x7fffffff, v147
	v_mul_f32_e32 v165, v148, v148
	v_mul_f32_e32 v168, v142, v142
	v_mul_f32_e32 v171, v143, v143
; __device__ __forceinline__ unsigned cvt_pk_bf16(float lo, float hi) { const f32x2 v = {lo, hi}; const bf16v2_t b = __builtin_convertvector(v, bf16v2_t); return __builtin_bit_cast(unsigned, b); }
; __device__ __forceinline__ float sigmoidf_(float x) { return __builtin_amdgcn_rcpf(1.0f + __builtin_amdgcn_exp2f(x * -1.44269504089f)); }
; __device__ __forceinline__ float siluf_(float x) { return x * __builtin_amdgcn_rcpf(1.0f + __builtin_amdgcn_exp2f(x * -1.44269504089f)); }
; __device__ __forceinline__ f32x2 gelu_pk(f32x2 v) {
;     const f32x2 av = __builtin_elementwise_abs(v), d = av * 0.2316418882f + 1.0f;
;     f32x2 t; t.x = __builtin_amdgcn_rcpf(d.x); t.y = __builtin_amdgcn_rcpf(d.y);
;     f32x2 q = t * 0.5307027145f + (-0.7265760135f); q = q * t + 0.7107068705f; q = q * t + (-0.142248368f); q = q * t + 0.127414796f; q = q * t;
;     const f32x2 s = (v * v) * (-0.72134752044f);
;     f32x2 e; e.x = __builtin_amdgcn_exp2f(s.x); e.y = __builtin_amdgcn_exp2f(s.y);
;     const f32x2 m = v * (q * e), r = v - m;
;     f32x2 o; o.x = v.x < 0.f ? m.x : r.x; o.y = v.y < 0.f ? m.y : r.y; return o;
;     __device__ __forceinline__ void epi_proj(const f32x4 (&acc)[2][2][4][2], const pg8::Unit& u, int wr, int wc, int fr, int fq) const {
;     ...
;                             f32x4 v0 = acc[ai][bj][m][0] * rstd, v1 = acc[ai][bj][m][1] * rstd;
;                             if (slot < 2) {
;                                 f32x2 a = gelu_pk((f32x2){v0[0], v0[1]}), b = gelu_pk((f32x2){v0[2], v0[3]}), c = gelu_pk((f32x2){v1[0], v1[1]}), d = gelu_pk((f32x2){v1[2], v1[3]});
;                                 v0 = (f32x4){a.x, a.y, b.x, b.y}; v1 = (f32x4){c.x, c.y, d.x, d.y};
;                             } else if (slot == 5) {
; #pragma unroll
;                                 for (int j = 0; j < 4; ++j) { v0[j] = siluf_(v0[j]); v1[j] = siluf_(v1[j]); }
;                             } else if (slot >= 6) {
; #pragma unroll
;                                 for (int j = 0; j < 4; ++j) { v0[j] = sigmoidf_(v0[j]); v1[j] = sigmoidf_(v1[j]); }
;                             }
;                             u32x4 w; w.x = cvt_pk_bf16(v0[0], v0[1]); w.y = cvt_pk_bf16(v0[2], v0[3]); w.z = cvt_pk_bf16(v1[0], v1[1]); w.w = cvt_pk_bf16(v1[2], v1[3]);
;                             *(u32x4*)(rowp + bj * 128) = w;
	v_mul_f32_e32 v174, v149, v149
	v_mul_f32_e32 v177, v140, v140
	v_mul_f32_e32 v180, v146, v146
	v_mul_f32_e32 v183, v141, v141
	v_mul_f32_e32 v186, v147, v147
	v_fma_f32 v164, v164, s14, 1.0
	v_fma_f32 v167, v167, s14, 1.0
	v_fma_f32 v170, v170, s14, 1.0
	v_fma_f32 v173, v173, s14, 1.0
	v_fma_f32 v176, v176, s14, 1.0
	v_fma_f32 v179, v179, s14, 1.0
	v_fma_f32 v182, v182, s14, 1.0
	v_fma_f32 v185, v185, s14, 1.0
	v_mul_f32_e32 v165, s20, v165
	v_mul_f32_e32 v168, s20, v168
	v_mul_f32_e32 v171, s20, v171
	v_mul_f32_e32 v174, s20, v174
	v_mul_f32_e32 v177, s20, v177
	v_mul_f32_e32 v180, s20, v180
	v_mul_f32_e32 v183, s20, v183
	v_mul_f32_e32 v186, s20, v186
	v_rcp_f32_e32 v164, v164
	v_rcp_f32_e32 v167, v167
	v_rcp_f32_e32 v170, v170
	v_rcp_f32_e32 v173, v173
	v_rcp_f32_e32 v176, v176
	v_rcp_f32_e32 v179, v179
	v_rcp_f32_e32 v182, v182
	v_rcp_f32_e32 v185, v185
	s_nop 0
	v_exp_f32_e32 v165, v165
	v_exp_f32_e32 v168, v168
	v_exp_f32_e32 v171, v171
	v_exp_f32_e32 v174, v174
	v_exp_f32_e32 v177, v177
	v_exp_f32_e32 v180, v180
	v_exp_f32_e32 v183, v183
	v_exp_f32_e32 v186, v186
	s_nop 0
	v_fma_f32 v166, v164, s15, v188
	v_fma_f32 v169, v167, s15, v188
	v_fma_f32 v172, v170, s15, v188
	v_fma_f32 v175, v173, s15, v188
	v_fma_f32 v178, v176, s15, v188
	v_fma_f32 v181, v179, s15, v188
	v_fma_f32 v184, v182, s15, v188
	v_fma_f32 v187, v185, s15, v188
	v_fma_f32 v166, v166, v164, v189
	v_fma_f32 v169, v169, v167, v189
	v_fma_f32 v172, v172, v170, v189
	v_fma_f32 v175, v175, v173, v189
	v_fma_f32 v178, v178, v176, v189
	v_fma_f32 v181, v181, v179, v189
	v_fma_f32 v184, v184, v182, v189
	v_fma_f32 v187, v187, v185, v189
	v_fma_f32 v166, v166, v164, v190
	v_fma_f32 v169, v169, v167, v190
	v_fma_f32 v172, v172, v170, v190
	v_fma_f32 v175, v175, v173, v190
	v_fma_f32 v178, v178, v176, v190
	v_fma_f32 v181, v181, v179, v190
	v_fma_f32 v184, v184, v182, v190
	v_fma_f32 v187, v187, v185, v190
	v_fma_f32 v166, v166, v164, v191
	v_fma_f32 v169, v169, v167, v191
	v_fma_f32 v172, v172, v170, v191
	v_fma_f32 v175, v175, v173, v191
	v_fma_f32 v178, v178, v176, v191
	v_fma_f32 v181, v181, v179, v191
	v_fma_f32 v184, v184, v182, v191
	v_fma_f32 v187, v187, v185, v191
	v_mul_f32_e32 v166, v166, v164
	v_mul_f32_e32 v169, v169, v167
	v_mul_f32_e32 v172, v172, v170
	v_mul_f32_e32 v175, v175, v173
	v_mul_f32_e32 v178, v178, v176
	v_mul_f32_e32 v181, v181, v179
	v_mul_f32_e32 v184, v184, v182
	v_mul_f32_e32 v187, v187, v185
	v_mul_f32_e32 v166, v166, v165
	v_mul_f32_e32 v169, v169, v168
	v_mul_f32_e32 v172, v172, v171
	v_mul_f32_e32 v175, v175, v174
	v_mul_f32_e32 v178, v178, v177
	v_mul_f32_e32 v181, v181, v180
	v_mul_f32_e32 v184, v184, v183
	v_mul_f32_e32 v187, v187, v186
	v_mul_f32_e32 v166, v148, v166
	v_mul_f32_e32 v169, v142, v169
	v_mul_f32_e32 v172, v143, v172
	v_mul_f32_e32 v175, v149, v175
	v_mul_f32_e32 v178, v140, v178
	v_mul_f32_e32 v181, v146, v181
	v_mul_f32_e32 v184, v141, v184
	v_mul_f32_e32 v187, v147, v187
	v_sub_f32_e32 v165, v148, v166
	v_sub_f32_e32 v168, v142, v169
	v_sub_f32_e32 v171, v143, v172
	v_sub_f32_e32 v174, v149, v175
	v_sub_f32_e32 v177, v140, v178
	v_sub_f32_e32 v180, v146, v181
	v_sub_f32_e32 v183, v141, v184
	v_sub_f32_e32 v186, v147, v187
	v_cmp_gt_f32_e64 s[100:101], 0, v148
	s_nop 1
	v_cndmask_b32_e64 v148, v165, v166, s[100:101]
	v_cmp_gt_f32_e64 s[100:101], 0, v142
	s_nop 1
	v_cndmask_b32_e64 v142, v168, v169, s[100:101]
	v_cmp_gt_f32_e64 s[100:101], 0, v143
	s_nop 1
	v_cndmask_b32_e64 v143, v171, v172, s[100:101]
	v_cmp_gt_f32_e64 s[100:101], 0, v149
	s_nop 1
	v_cndmask_b32_e64 v149, v174, v175, s[100:101]
	v_cmp_gt_f32_e64 s[100:101], 0, v140
	s_nop 1
	v_cndmask_b32_e64 v140, v177, v178, s[100:101]
	v_cmp_gt_f32_e64 s[100:101], 0, v146
	s_nop 1
	v_cndmask_b32_e64 v146, v180, v181, s[100:101]
	v_cmp_gt_f32_e64 s[100:101], 0, v141
	s_nop 1
	v_cndmask_b32_e64 v141, v183, v184, s[100:101]
	v_cmp_gt_f32_e64 s[100:101], 0, v147
	s_nop 1
	v_cndmask_b32_e64 v147, v186, v187, s[100:101]
	v_mov_b32_e32 v150, v140
	v_mov_b32_e32 v151, v141
	v_cvt_pk_bf16_f32 v140, v142, v143
	v_cvt_pk_bf16_f32 v141, v150, v151
	v_cvt_pk_bf16_f32 v142, v148, v149
	v_cvt_pk_bf16_f32 v143, v146, v147
	global_store_dwordx4 v[144:145], v[140:143], off
	v_pk_mul_f32 v[146:147], v[74:75], v[138:139] op_sel_hi:[1,0]
	v_mul_f32_e32 v129, 0x45800000, v128
	v_pk_mul_f32 v[140:141], v[78:79], v[138:139] op_sel_hi:[1,0]
	v_pk_mul_f32 v[142:143], v[76:77], v[138:139] op_sel_hi:[1,0]
	v_pk_mul_f32 v[138:139], v[72:73], v[138:139] op_sel_hi:[1,0]
	v_and_b32_e32 v164, 0x7fffffff, v142
	v_and_b32_e32 v167, 0x7fffffff, v138
	v_and_b32_e32 v170, 0x7fffffff, v139
	v_and_b32_e32 v173, 0x7fffffff, v143
	v_mul_f32_e32 v165, v142, v142
	v_mul_f32_e32 v168, v138, v138
	v_mul_f32_e32 v171, v139, v139
	v_mul_f32_e32 v174, v143, v143
	v_fma_f32 v164, v164, s14, 1.0
	v_fma_f32 v167, v167, s14, 1.0
	v_fma_f32 v170, v170, s14, 1.0
	v_fma_f32 v173, v173, s14, 1.0
	v_mul_f32_e32 v165, s20, v165
	v_mul_f32_e32 v168, s20, v168
	v_mul_f32_e32 v171, s20, v171
	v_mul_f32_e32 v174, s20, v174
	v_rcp_f32_e32 v164, v164
	v_rcp_f32_e32 v167, v167
	v_rcp_f32_e32 v170, v170
	v_rcp_f32_e32 v173, v173
	s_nop 0
	v_exp_f32_e32 v165, v165
	v_exp_f32_e32 v168, v168
	v_exp_f32_e32 v171, v171
	v_exp_f32_e32 v174, v174
	s_nop 0
	v_fma_f32 v166, v164, s15, v188
	v_fma_f32 v169, v167, s15, v188
	v_fma_f32 v172, v170, s15, v188
	v_fma_f32 v175, v173, s15, v188
	v_fma_f32 v166, v166, v164, v189
	v_fma_f32 v169, v169, v167, v189
	v_fma_f32 v172, v172, v170, v189
	v_fma_f32 v175, v175, v173, v189
	v_fma_f32 v166, v166, v164, v190
	v_fma_f32 v169, v169, v167, v190
	v_fma_f32 v172, v172, v170, v190
; __device__ __forceinline__ unsigned cvt_pk_bf16(float lo, float hi) { const f32x2 v = {lo, hi}; const bf16v2_t b = __builtin_convertvector(v, bf16v2_t); return __builtin_bit_cast(unsigned, b); }
; __device__ __forceinline__ float sigmoidf_(float x) { return __builtin_amdgcn_rcpf(1.0f + __builtin_amdgcn_exp2f(x * -1.44269504089f)); }
; __device__ __forceinline__ float siluf_(float x) { return x * __builtin_amdgcn_rcpf(1.0f + __builtin_amdgcn_exp2f(x * -1.44269504089f)); }
; __device__ __forceinline__ f32x2 gelu_pk(f32x2 v) {
;     const f32x2 av = __builtin_elementwise_abs(v), d = av * 0.2316418882f + 1.0f;
;     f32x2 t; t.x = __builtin_amdgcn_rcpf(d.x); t.y = __builtin_amdgcn_rcpf(d.y);
;     f32x2 q = t * 0.5307027145f + (-0.7265760135f); q = q * t + 0.7107068705f; q = q * t + (-0.142248368f); q = q * t + 0.127414796f; q = q * t;
;     const f32x2 s = (v * v) * (-0.72134752044f);
;     f32x2 e; e.x = __builtin_amdgcn_exp2f(s.x); e.y = __builtin_amdgcn_exp2f(s.y);
;     const f32x2 m = v * (q * e), r = v - m;
;     f32x2 o; o.x = v.x < 0.f ? m.x : r.x; o.y = v.y < 0.f ? m.y : r.y; return o;
;     __device__ __forceinline__ void epi_proj(const f32x4 (&acc)[2][2][4][2], const pg8::Unit& u, int wr, int wc, int fr, int fq) const {
;     ...
;                             f32x4 v0 = acc[ai][bj][m][0] * rstd, v1 = acc[ai][bj][m][1] * rstd;
;                             if (slot < 2) {
;                                 f32x2 a = gelu_pk((f32x2){v0[0], v0[1]}), b = gelu_pk((f32x2){v0[2], v0[3]}), c = gelu_pk((f32x2){v1[0], v1[1]}), d = gelu_pk((f32x2){v1[2], v1[3]});
;                                 v0 = (f32x4){a.x, a.y, b.x, b.y}; v1 = (f32x4){c.x, c.y, d.x, d.y};
;                             } else if (slot == 5) {
; #pragma unroll
;                                 for (int j = 0; j < 4; ++j) { v0[j] = siluf_(v0[j]); v1[j] = siluf_(v1[j]); }
;                             } else if (slot >= 6) {
; #pragma unroll
;                                 for (int j = 0; j < 4; ++j) { v0[j] = sigmoidf_(v0[j]); v1[j] = sigmoidf_(v1[j]); }
;                             }
;                             u32x4 w; w.x = cvt_pk_bf16(v0[0], v0[1]); w.y = cvt_pk_bf16(v0[2], v0[3]); w.z = cvt_pk_bf16(v1[0], v1[1]); w.w = cvt_pk_bf16(v1[2], v1[3]);
;                             *(u32x4*)(rowp + bj * 128) = w;
	v_fma_f32 v175, v175, v173, v190
	v_fma_f32 v166, v166, v164, v191
	v_fma_f32 v169, v169, v167, v191
	v_fma_f32 v172, v172, v170, v191
	v_fma_f32 v175, v175, v173, v191
	v_mul_f32_e32 v166, v166, v164
	v_mul_f32_e32 v169, v169, v167
	v_mul_f32_e32 v172, v172, v170
	v_mul_f32_e32 v175, v175, v173
	v_mul_f32_e32 v166, v166, v165
	v_mul_f32_e32 v169, v169, v168
	v_mul_f32_e32 v172, v172, v171
	v_mul_f32_e32 v175, v175, v174
	v_mul_f32_e32 v166, v142, v166
	v_mul_f32_e32 v169, v138, v169
	v_mul_f32_e32 v172, v139, v172
	v_mul_f32_e32 v175, v143, v175
	v_sub_f32_e32 v165, v142, v166
	v_sub_f32_e32 v168, v138, v169
	v_sub_f32_e32 v171, v139, v172
	v_sub_f32_e32 v174, v143, v175
	v_cmp_gt_f32_e64 s[100:101], 0, v142
	s_nop 1
	v_cndmask_b32_e64 v142, v165, v166, s[100:101]
	v_cmp_gt_f32_e64 s[100:101], 0, v138
	s_nop 1
	v_cndmask_b32_e64 v138, v168, v169, s[100:101]
	v_cmp_gt_f32_e64 s[100:101], 0, v139
	s_nop 1
	v_cndmask_b32_e64 v139, v171, v172, s[100:101]
	v_cmp_gt_f32_e64 s[100:101], 0, v143
	s_nop 1
	v_cndmask_b32_e64 v143, v174, v175, s[100:101]
	v_mov_b32_e32 v148, v138
	v_mov_b32_e32 v149, v139
	v_and_b32_e32 v164, 0x7fffffff, v140
	v_mul_f32_e32 v165, v140, v140
	v_fma_f32 v164, v164, s14, 1.0
	v_mul_f32_e32 v165, s20, v165
	v_rcp_f32_e32 v164, v164
	s_nop 0
	v_exp_f32_e32 v165, v165
	s_nop 0
	v_fma_f32 v166, v164, s15, v188
	v_fma_f32 v166, v166, v164, v189
	v_fma_f32 v166, v166, v164, v190
	v_fma_f32 v166, v166, v164, v191
	v_mul_f32_e32 v166, v166, v164
	v_mul_f32_e32 v166, v166, v165
	v_mul_f32_e32 v166, v140, v166
	v_sub_f32_e32 v165, v140, v166
	v_cmp_gt_f32_e64 s[100:101], 0, v140
	s_nop 1
	v_cndmask_b32_e64 v138, v165, v166, s[100:101]
	v_and_b32_e32 v164, 0x7fffffff, v146
	v_and_b32_e32 v167, 0x7fffffff, v141
	v_mul_f32_e32 v165, v146, v146
	v_mul_f32_e32 v168, v141, v141
	v_fma_f32 v164, v164, s14, 1.0
	v_fma_f32 v167, v167, s14, 1.0
	v_mul_f32_e32 v165, s20, v165
	v_mul_f32_e32 v168, s20, v168
	v_rcp_f32_e32 v164, v164
	v_rcp_f32_e32 v167, v167
	s_nop 0
	v_exp_f32_e32 v165, v165
	v_exp_f32_e32 v168, v168
	s_nop 0
	v_fma_f32 v166, v164, s15, v188
	v_fma_f32 v169, v167, s15, v188
	v_fma_f32 v166, v166, v164, v189
	v_fma_f32 v169, v169, v167, v189
	v_fma_f32 v166, v166, v164, v190
	v_fma_f32 v169, v169, v167, v190
	v_fma_f32 v166, v166, v164, v191
	v_fma_f32 v169, v169, v167, v191
	v_mul_f32_e32 v166, v166, v164
	v_mul_f32_e32 v169, v169, v167
	v_mul_f32_e32 v166, v166, v165
	v_mul_f32_e32 v169, v169, v168
	v_mul_f32_e32 v166, v146, v166
	v_mul_f32_e32 v169, v141, v169
	v_sub_f32_e32 v165, v146, v166
	v_sub_f32_e32 v168, v141, v169
	v_cmp_gt_f32_e64 s[100:101], 0, v146
	s_nop 1
	v_cndmask_b32_e64 v140, v165, v166, s[100:101]
	v_cmp_gt_f32_e64 s[100:101], 0, v141
	s_nop 1
	v_cndmask_b32_e64 v139, v168, v169, s[100:101]
	v_mov_b32_e32 v150, v138
	v_mov_b32_e32 v151, v139
	v_and_b32_e32 v164, 0x7fffffff, v147
	v_mul_f32_e32 v165, v147, v147
	v_fma_f32 v164, v164, s14, 1.0
	v_mul_f32_e32 v165, s20, v165
	v_rcp_f32_e32 v164, v164
	s_nop 0
	v_exp_f32_e32 v165, v165
	s_nop 0
	v_fma_f32 v166, v164, s15, v188
	v_fma_f32 v166, v166, v164, v189
	v_fma_f32 v166, v166, v164, v190
	v_fma_f32 v166, v166, v164, v191
	v_mul_f32_e32 v166, v166, v164
	v_mul_f32_e32 v166, v166, v165
	v_mul_f32_e32 v166, v147, v166
	v_sub_f32_e32 v165, v147, v166
	v_cmp_gt_f32_e64 s[100:101], 0, v147
	s_nop 1
	v_cndmask_b32_e64 v141, v165, v166, s[100:101]
	v_mov_b32_e32 v146, v140
	v_mov_b32_e32 v147, v141
	v_cvt_pk_bf16_f32 v138, v142, v143
	v_cvt_pk_bf16_f32 v139, v150, v151
	v_cvt_pk_bf16_f32 v140, v148, v149
	v_cvt_pk_bf16_f32 v141, v146, v147
	global_store_dwordx4 v[144:145], v[138:141], off offset:256
	v_pk_mul_f32 v[144:145], v[50:51], v[134:135] op_sel_hi:[1,0]
	v_pk_mul_f32 v[146:147], v[48:49], v[134:135] op_sel_hi:[1,0]
	v_pk_mul_f32 v[140:141], v[52:53], v[134:135] op_sel_hi:[1,0]
	v_pk_mul_f32 v[138:139], v[54:55], v[134:135] op_sel_hi:[1,0]
	v_lshl_add_u64 v[142:143], v[136:137], 0, s[0:1]
	v_and_b32_e32 v164, 0x7fffffff, v140
	v_and_b32_e32 v167, 0x7fffffff, v141
	v_and_b32_e32 v170, 0x7fffffff, v144
	v_and_b32_e32 v173, 0x7fffffff, v145
	v_and_b32_e32 v176, 0x7fffffff, v146
	v_mul_f32_e32 v165, v140, v140
	v_mul_f32_e32 v168, v141, v141
	v_mul_f32_e32 v171, v144, v144
	v_mul_f32_e32 v174, v145, v145
	v_mul_f32_e32 v177, v146, v146
	v_fma_f32 v164, v164, s14, 1.0
	v_fma_f32 v167, v167, s14, 1.0
	v_fma_f32 v170, v170, s14, 1.0
	v_fma_f32 v173, v173, s14, 1.0
	v_fma_f32 v176, v176, s14, 1.0
	v_mul_f32_e32 v165, s20, v165
	v_mul_f32_e32 v168, s20, v168
	v_mul_f32_e32 v171, s20, v171
	v_mul_f32_e32 v174, s20, v174
	v_mul_f32_e32 v177, s20, v177
	v_rcp_f32_e32 v164, v164
	v_rcp_f32_e32 v167, v167
	v_rcp_f32_e32 v170, v170
	v_rcp_f32_e32 v173, v173
	v_rcp_f32_e32 v176, v176
	s_nop 0
	v_exp_f32_e32 v165, v165
	v_exp_f32_e32 v168, v168
	v_exp_f32_e32 v171, v171
	v_exp_f32_e32 v174, v174
	v_exp_f32_e32 v177, v177
	s_nop 0
	v_fma_f32 v166, v164, s15, v188
	v_fma_f32 v169, v167, s15, v188
	v_fma_f32 v172, v170, s15, v188
	v_fma_f32 v175, v173, s15, v188
	v_fma_f32 v178, v176, s15, v188
	v_fma_f32 v166, v166, v164, v189
	v_fma_f32 v169, v169, v167, v189
	v_fma_f32 v172, v172, v170, v189
	v_fma_f32 v175, v175, v173, v189
	v_fma_f32 v178, v178, v176, v189
	v_fma_f32 v166, v166, v164, v190
	v_fma_f32 v169, v169, v167, v190
	v_fma_f32 v172, v172, v170, v190
	v_fma_f32 v175, v175, v173, v190
	v_fma_f32 v178, v178, v176, v190
	v_fma_f32 v166, v166, v164, v191
	v_fma_f32 v169, v169, v167, v191
	v_fma_f32 v172, v172, v170, v191
	v_fma_f32 v175, v175, v173, v191
	v_fma_f32 v178, v178, v176, v191
	v_mul_f32_e32 v166, v166, v164
	v_mul_f32_e32 v169, v169, v167
; __device__ __forceinline__ unsigned cvt_pk_bf16(float lo, float hi) { const f32x2 v = {lo, hi}; const bf16v2_t b = __builtin_convertvector(v, bf16v2_t); return __builtin_bit_cast(unsigned, b); }
; __device__ __forceinline__ float sigmoidf_(float x) { return __builtin_amdgcn_rcpf(1.0f + __builtin_amdgcn_exp2f(x * -1.44269504089f)); }
; __device__ __forceinline__ float siluf_(float x) { return x * __builtin_amdgcn_rcpf(1.0f + __builtin_amdgcn_exp2f(x * -1.44269504089f)); }
; __device__ __forceinline__ f32x2 gelu_pk(f32x2 v) {
;     const f32x2 av = __builtin_elementwise_abs(v), d = av * 0.2316418882f + 1.0f;
;     f32x2 t; t.x = __builtin_amdgcn_rcpf(d.x); t.y = __builtin_amdgcn_rcpf(d.y);
;     f32x2 q = t * 0.5307027145f + (-0.7265760135f); q = q * t + 0.7107068705f; q = q * t + (-0.142248368f); q = q * t + 0.127414796f; q = q * t;
;     const f32x2 s = (v * v) * (-0.72134752044f);
;     f32x2 e; e.x = __builtin_amdgcn_exp2f(s.x); e.y = __builtin_amdgcn_exp2f(s.y);
;     const f32x2 m = v * (q * e), r = v - m;
;     f32x2 o; o.x = v.x < 0.f ? m.x : r.x; o.y = v.y < 0.f ? m.y : r.y; return o;
;     __device__ __forceinline__ void epi_proj(const f32x4 (&acc)[2][2][4][2], const pg8::Unit& u, int wr, int wc, int fr, int fq) const {
;     ...
;                             f32x4 v0 = acc[ai][bj][m][0] * rstd, v1 = acc[ai][bj][m][1] * rstd;
;                             if (slot < 2) {
;                                 f32x2 a = gelu_pk((f32x2){v0[0], v0[1]}), b = gelu_pk((f32x2){v0[2], v0[3]}), c = gelu_pk((f32x2){v1[0], v1[1]}), d = gelu_pk((f32x2){v1[2], v1[3]});
;                                 v0 = (f32x4){a.x, a.y, b.x, b.y}; v1 = (f32x4){c.x, c.y, d.x, d.y};
;                             } else if (slot == 5) {
; #pragma unroll
;                                 for (int j = 0; j < 4; ++j) { v0[j] = siluf_(v0[j]); v1[j] = siluf_(v1[j]); }
;                             } else if (slot >= 6) {
; #pragma unroll
;                                 for (int j = 0; j < 4; ++j) { v0[j] = sigmoidf_(v0[j]); v1[j] = sigmoidf_(v1[j]); }
;                             }
;                             u32x4 w; w.x = cvt_pk_bf16(v0[0], v0[1]); w.y = cvt_pk_bf16(v0[2], v0[3]); w.z = cvt_pk_bf16(v1[0], v1[1]); w.w = cvt_pk_bf16(v1[2], v1[3]);
;                             *(u32x4*)(rowp + bj * 128) = w;
	v_mul_f32_e32 v172, v172, v170
	v_mul_f32_e32 v175, v175, v173
	v_mul_f32_e32 v178, v178, v176
	v_mul_f32_e32 v166, v166, v165
	v_mul_f32_e32 v169, v169, v168
	v_mul_f32_e32 v172, v172, v171
	v_mul_f32_e32 v175, v175, v174
	v_mul_f32_e32 v178, v178, v177
	v_mul_f32_e32 v166, v140, v166
	v_mul_f32_e32 v169, v141, v169
	v_mul_f32_e32 v172, v144, v172
	v_mul_f32_e32 v175, v145, v175
	v_mul_f32_e32 v178, v146, v178
	v_sub_f32_e32 v165, v140, v166
	v_sub_f32_e32 v168, v141, v169
	v_sub_f32_e32 v171, v144, v172
	v_sub_f32_e32 v174, v145, v175
	v_sub_f32_e32 v177, v146, v178
	v_cmp_gt_f32_e64 s[100:101], 0, v140
	s_nop 1
	v_cndmask_b32_e64 v140, v165, v166, s[100:101]
	v_cmp_gt_f32_e64 s[100:101], 0, v141
	s_nop 1
	v_cndmask_b32_e64 v141, v168, v169, s[100:101]
	v_cmp_gt_f32_e64 s[100:101], 0, v144
	s_nop 1
	v_cndmask_b32_e64 v144, v171, v172, s[100:101]
	v_cmp_gt_f32_e64 s[100:101], 0, v145
	s_nop 1
	v_cndmask_b32_e64 v145, v174, v175, s[100:101]
	v_cmp_gt_f32_e64 s[100:101], 0, v146
	s_nop 1
	v_cndmask_b32_e64 v146, v177, v178, s[100:101]
	s_mov_b32 s0, 0x40000
	v_cndmask_b32_e32 v128, v128, v129, vcc
	v_and_b32_e32 v164, 0x7fffffff, v147
	v_and_b32_e32 v167, 0x7fffffff, v138
	v_and_b32_e32 v170, 0x7fffffff, v139
	v_mul_f32_e32 v165, v147, v147
	v_mul_f32_e32 v168, v138, v138
	v_mul_f32_e32 v171, v139, v139
	v_fma_f32 v164, v164, s14, 1.0
	v_fma_f32 v167, v167, s14, 1.0
	v_fma_f32 v170, v170, s14, 1.0
	v_mul_f32_e32 v165, s20, v165
	v_mul_f32_e32 v168, s20, v168
	v_mul_f32_e32 v171, s20, v171
	v_rcp_f32_e32 v164, v164
	v_rcp_f32_e32 v167, v167
	v_rcp_f32_e32 v170, v170
	s_nop 0
	v_exp_f32_e32 v165, v165
	v_exp_f32_e32 v168, v168
	v_exp_f32_e32 v171, v171
	s_nop 0
	v_fma_f32 v166, v164, s15, v188
	v_fma_f32 v169, v167, s15, v188
	v_fma_f32 v172, v170, s15, v188
	v_fma_f32 v166, v166, v164, v189
	v_fma_f32 v169, v169, v167, v189
	v_fma_f32 v172, v172, v170, v189
	v_fma_f32 v166, v166, v164, v190
	v_fma_f32 v169, v169, v167, v190
	v_fma_f32 v172, v172, v170, v190
	v_fma_f32 v166, v166, v164, v191
	v_fma_f32 v169, v169, v167, v191
	v_fma_f32 v172, v172, v170, v191
	v_mul_f32_e32 v166, v166, v164
	v_mul_f32_e32 v169, v169, v167
	v_mul_f32_e32 v172, v172, v170
	v_mul_f32_e32 v166, v166, v165
	v_mul_f32_e32 v169, v169, v168
	v_mul_f32_e32 v172, v172, v171
	v_mul_f32_e32 v166, v147, v166
	v_mul_f32_e32 v169, v138, v169
	v_mul_f32_e32 v172, v139, v172
	v_sub_f32_e32 v165, v147, v166
	v_sub_f32_e32 v168, v138, v169
	v_sub_f32_e32 v171, v139, v172
	v_cmp_gt_f32_e64 s[100:101], 0, v147
	s_nop 1
	v_cndmask_b32_e64 v147, v165, v166, s[100:101]
	v_cmp_gt_f32_e64 s[100:101], 0, v138
	s_nop 1
	v_cndmask_b32_e64 v138, v168, v169, s[100:101]
	v_cmp_gt_f32_e64 s[100:101], 0, v139
	s_nop 1
	v_cndmask_b32_e64 v139, v171, v172, s[100:101]
	v_mov_b32_e32 v148, v138
	v_mov_b32_e32 v149, v139
	v_cvt_pk_bf16_f32 v138, v140, v141
	v_cvt_pk_bf16_f32 v141, v144, v145
	v_add_co_u32_e32 v144, vcc, s0, v136
	v_cvt_pk_bf16_f32 v139, v148, v149
	v_cvt_pk_bf16_f32 v140, v146, v147
	v_addc_co_u32_e32 v145, vcc, 0, v137, vcc
	global_store_dwordx4 v[144:145], v[138:141], off
	v_pk_mul_f32 v[144:145], v[58:59], v[134:135] op_sel_hi:[1,0]
	s_mov_b64 s[0:1], 0x48000
	v_pk_mul_f32 v[138:139], v[62:63], v[134:135] op_sel_hi:[1,0]
	v_pk_mul_f32 v[140:141], v[60:61], v[134:135] op_sel_hi:[1,0]
	v_pk_mul_f32 v[134:135], v[56:57], v[134:135] op_sel_hi:[1,0]
	v_and_b32_e32 v164, 0x7fffffff, v140
	v_and_b32_e32 v167, 0x7fffffff, v134
	v_and_b32_e32 v170, 0x7fffffff, v141
	v_and_b32_e32 v173, 0x7fffffff, v135
	v_and_b32_e32 v176, 0x7fffffff, v138
	v_and_b32_e32 v179, 0x7fffffff, v144
	v_and_b32_e32 v182, 0x7fffffff, v139
	v_and_b32_e32 v185, 0x7fffffff, v145
	v_mul_f32_e32 v165, v140, v140
	v_mul_f32_e32 v168, v134, v134
	v_mul_f32_e32 v171, v141, v141
	v_mul_f32_e32 v174, v135, v135
	v_mul_f32_e32 v177, v138, v138
	v_mul_f32_e32 v180, v144, v144
	v_mul_f32_e32 v183, v139, v139
	v_mul_f32_e32 v186, v145, v145
	v_fma_f32 v164, v164, s14, 1.0
	v_fma_f32 v167, v167, s14, 1.0
	v_fma_f32 v170, v170, s14, 1.0
	v_fma_f32 v173, v173, s14, 1.0
	v_fma_f32 v176, v176, s14, 1.0
	v_fma_f32 v179, v179, s14, 1.0
	v_fma_f32 v182, v182, s14, 1.0
	v_fma_f32 v185, v185, s14, 1.0
	v_mul_f32_e32 v165, s20, v165
	v_mul_f32_e32 v168, s20, v168
	v_mul_f32_e32 v171, s20, v171
	v_mul_f32_e32 v174, s20, v174
	v_mul_f32_e32 v177, s20, v177
	v_mul_f32_e32 v180, s20, v180
	v_mul_f32_e32 v183, s20, v183
	v_mul_f32_e32 v186, s20, v186
	v_rcp_f32_e32 v164, v164
	v_rcp_f32_e32 v167, v167
	v_rcp_f32_e32 v170, v170
	v_rcp_f32_e32 v173, v173
	v_rcp_f32_e32 v176, v176
	v_rcp_f32_e32 v179, v179
	v_rcp_f32_e32 v182, v182
	v_rcp_f32_e32 v185, v185
	s_nop 0
	v_exp_f32_e32 v165, v165
	v_exp_f32_e32 v168, v168
	v_exp_f32_e32 v171, v171
	v_exp_f32_e32 v174, v174
	v_exp_f32_e32 v177, v177
	v_exp_f32_e32 v180, v180
	v_exp_f32_e32 v183, v183
	v_exp_f32_e32 v186, v186
	s_nop 0
	v_fma_f32 v166, v164, s15, v188
	v_fma_f32 v169, v167, s15, v188
	v_fma_f32 v172, v170, s15, v188
	v_fma_f32 v175, v173, s15, v188
	v_fma_f32 v178, v176, s15, v188
	v_fma_f32 v181, v179, s15, v188
	v_fma_f32 v184, v182, s15, v188
	v_fma_f32 v187, v185, s15, v188
	v_fma_f32 v166, v166, v164, v189
	v_fma_f32 v169, v169, v167, v189
	v_fma_f32 v172, v172, v170, v189
	v_fma_f32 v175, v175, v173, v189
	v_fma_f32 v178, v178, v176, v189
	v_fma_f32 v181, v181, v179, v189
	v_fma_f32 v184, v184, v182, v189
	v_fma_f32 v187, v187, v185, v189
	v_fma_f32 v166, v166, v164, v190
	v_fma_f32 v169, v169, v167, v190
	v_fma_f32 v172, v172, v170, v190
	v_fma_f32 v175, v175, v173, v190
	v_fma_f32 v178, v178, v176, v190
	v_fma_f32 v181, v181, v179, v190
	v_fma_f32 v184, v184, v182, v190
; __device__ __forceinline__ unsigned cvt_pk_bf16(float lo, float hi) { const f32x2 v = {lo, hi}; const bf16v2_t b = __builtin_convertvector(v, bf16v2_t); return __builtin_bit_cast(unsigned, b); }
; __device__ __forceinline__ float sigmoidf_(float x) { return __builtin_amdgcn_rcpf(1.0f + __builtin_amdgcn_exp2f(x * -1.44269504089f)); }
; __device__ __forceinline__ float siluf_(float x) { return x * __builtin_amdgcn_rcpf(1.0f + __builtin_amdgcn_exp2f(x * -1.44269504089f)); }
; __device__ __forceinline__ f32x2 gelu_pk(f32x2 v) {
;     const f32x2 av = __builtin_elementwise_abs(v), d = av * 0.2316418882f + 1.0f;
;     f32x2 t; t.x = __builtin_amdgcn_rcpf(d.x); t.y = __builtin_amdgcn_rcpf(d.y);
;     f32x2 q = t * 0.5307027145f + (-0.7265760135f); q = q * t + 0.7107068705f; q = q * t + (-0.142248368f); q = q * t + 0.127414796f; q = q * t;
;     const f32x2 s = (v * v) * (-0.72134752044f);
;     f32x2 e; e.x = __builtin_amdgcn_exp2f(s.x); e.y = __builtin_amdgcn_exp2f(s.y);
;     const f32x2 m = v * (q * e), r = v - m;
;     f32x2 o; o.x = v.x < 0.f ? m.x : r.x; o.y = v.y < 0.f ? m.y : r.y; return o;
;     __device__ __forceinline__ void epi_proj(const f32x4 (&acc)[2][2][4][2], const pg8::Unit& u, int wr, int wc, int fr, int fq) const {
;     ...
;                             f32x4 v0 = acc[ai][bj][m][0] * rstd, v1 = acc[ai][bj][m][1] * rstd;
;                             if (slot < 2) {
;                                 f32x2 a = gelu_pk((f32x2){v0[0], v0[1]}), b = gelu_pk((f32x2){v0[2], v0[3]}), c = gelu_pk((f32x2){v1[0], v1[1]}), d = gelu_pk((f32x2){v1[2], v1[3]});
;                                 v0 = (f32x4){a.x, a.y, b.x, b.y}; v1 = (f32x4){c.x, c.y, d.x, d.y};
;                             } else if (slot == 5) {
; #pragma unroll
;                                 for (int j = 0; j < 4; ++j) { v0[j] = siluf_(v0[j]); v1[j] = siluf_(v1[j]); }
;                             } else if (slot >= 6) {
; #pragma unroll
;                                 for (int j = 0; j < 4; ++j) { v0[j] = sigmoidf_(v0[j]); v1[j] = sigmoidf_(v1[j]); }
;                             }
;                             u32x4 w; w.x = cvt_pk_bf16(v0[0], v0[1]); w.y = cvt_pk_bf16(v0[2], v0[3]); w.z = cvt_pk_bf16(v1[0], v1[1]); w.w = cvt_pk_bf16(v1[2], v1[3]);
;                             *(u32x4*)(rowp + bj * 128) = w;
	v_fma_f32 v187, v187, v185, v190
	v_fma_f32 v166, v166, v164, v191
	v_fma_f32 v169, v169, v167, v191
	v_fma_f32 v172, v172, v170, v191
	v_fma_f32 v175, v175, v173, v191
	v_fma_f32 v178, v178, v176, v191
	v_fma_f32 v181, v181, v179, v191
	v_fma_f32 v184, v184, v182, v191
	v_fma_f32 v187, v187, v185, v191
	v_mul_f32_e32 v166, v166, v164
	v_mul_f32_e32 v169, v169, v167
	v_mul_f32_e32 v172, v172, v170
	v_mul_f32_e32 v175, v175, v173
	v_mul_f32_e32 v178, v178, v176
	v_mul_f32_e32 v181, v181, v179
	v_mul_f32_e32 v184, v184, v182
	v_mul_f32_e32 v187, v187, v185
	v_mul_f32_e32 v166, v166, v165
	v_mul_f32_e32 v169, v169, v168
	v_mul_f32_e32 v172, v172, v171
	v_mul_f32_e32 v175, v175, v174
	v_mul_f32_e32 v178, v178, v177
	v_mul_f32_e32 v181, v181, v180
	v_mul_f32_e32 v184, v184, v183
	v_mul_f32_e32 v187, v187, v186
	v_mul_f32_e32 v166, v140, v166
	v_mul_f32_e32 v169, v134, v169
	v_mul_f32_e32 v172, v141, v172
	v_mul_f32_e32 v175, v135, v175
	v_mul_f32_e32 v178, v138, v178
	v_mul_f32_e32 v181, v144, v181
	v_mul_f32_e32 v184, v139, v184
	v_mul_f32_e32 v187, v145, v187
	v_sub_f32_e32 v165, v140, v166
	v_sub_f32_e32 v168, v134, v169
	v_sub_f32_e32 v171, v141, v172
	v_sub_f32_e32 v174, v135, v175
	v_sub_f32_e32 v177, v138, v178
	v_sub_f32_e32 v180, v144, v181
	v_sub_f32_e32 v183, v139, v184
	v_sub_f32_e32 v186, v145, v187
	v_cmp_gt_f32_e64 s[100:101], 0, v140
	s_nop 1
	v_cndmask_b32_e64 v140, v165, v166, s[100:101]
	v_cmp_gt_f32_e64 s[100:101], 0, v134
	s_nop 1
	v_cndmask_b32_e64 v134, v168, v169, s[100:101]
	v_cmp_gt_f32_e64 s[100:101], 0, v141
	s_nop 1
	v_cndmask_b32_e64 v141, v171, v172, s[100:101]
	v_cmp_gt_f32_e64 s[100:101], 0, v135
	s_nop 1
	v_cndmask_b32_e64 v135, v174, v175, s[100:101]
	v_cmp_gt_f32_e64 s[100:101], 0, v138
	s_nop 1
	v_cndmask_b32_e64 v138, v177, v178, s[100:101]
	v_cmp_gt_f32_e64 s[100:101], 0, v144
	s_nop 1
	v_cndmask_b32_e64 v144, v180, v181, s[100:101]
	v_cmp_gt_f32_e64 s[100:101], 0, v139
	s_nop 1
	v_cndmask_b32_e64 v139, v183, v184, s[100:101]
	v_cmp_gt_f32_e64 s[100:101], 0, v145
	s_nop 1
	v_cndmask_b32_e64 v145, v186, v187, s[100:101]
	v_mov_b32_e32 v146, v138
	v_mov_b32_e32 v147, v139
	v_cvt_pk_bf16_f32 v138, v140, v141
	v_cvt_pk_bf16_f32 v139, v146, v147
	v_cvt_pk_bf16_f32 v140, v134, v135
	v_cvt_pk_bf16_f32 v141, v144, v145
	global_store_dwordx4 v[142:143], v[138:141], off offset:256
	v_pk_mul_f32 v[134:135], v[38:39], v[132:133] op_sel_hi:[1,0]
	v_pk_mul_f32 v[144:145], v[32:33], v[132:133] op_sel_hi:[1,0]
	v_pk_mul_f32 v[138:139], v[36:37], v[132:133] op_sel_hi:[1,0]
	v_pk_mul_f32 v[140:141], v[34:35], v[132:133] op_sel_hi:[1,0]
	v_lshl_add_u64 v[142:143], v[136:137], 0, s[0:1]
	v_and_b32_e32 v164, 0x7fffffff, v138
	v_and_b32_e32 v167, 0x7fffffff, v139
	v_and_b32_e32 v170, 0x7fffffff, v134
	v_and_b32_e32 v173, 0x7fffffff, v135
	v_and_b32_e32 v176, 0x7fffffff, v144
	v_mul_f32_e32 v165, v138, v138
	v_mul_f32_e32 v168, v139, v139
	v_mul_f32_e32 v171, v134, v134
	v_mul_f32_e32 v174, v135, v135
	v_mul_f32_e32 v177, v144, v144
	v_fma_f32 v164, v164, s14, 1.0
	v_fma_f32 v167, v167, s14, 1.0
	v_fma_f32 v170, v170, s14, 1.0
	v_fma_f32 v173, v173, s14, 1.0
	v_fma_f32 v176, v176, s14, 1.0
	v_mul_f32_e32 v165, s20, v165
	v_mul_f32_e32 v168, s20, v168
	v_mul_f32_e32 v171, s20, v171
	v_mul_f32_e32 v174, s20, v174
	v_mul_f32_e32 v177, s20, v177
	v_rcp_f32_e32 v164, v164
	v_rcp_f32_e32 v167, v167
	v_rcp_f32_e32 v170, v170
	v_rcp_f32_e32 v173, v173
	v_rcp_f32_e32 v176, v176
	s_nop 0
	v_exp_f32_e32 v165, v165
	v_exp_f32_e32 v168, v168
	v_exp_f32_e32 v171, v171
	v_exp_f32_e32 v174, v174
	v_exp_f32_e32 v177, v177
	s_nop 0
	v_fma_f32 v166, v164, s15, v188
	v_fma_f32 v169, v167, s15, v188
	v_fma_f32 v172, v170, s15, v188
	v_fma_f32 v175, v173, s15, v188
	v_fma_f32 v178, v176, s15, v188
	v_fma_f32 v166, v166, v164, v189
	v_fma_f32 v169, v169, v167, v189
	v_fma_f32 v172, v172, v170, v189
	v_fma_f32 v175, v175, v173, v189
	v_fma_f32 v178, v178, v176, v189
	v_fma_f32 v166, v166, v164, v190
	v_fma_f32 v169, v169, v167, v190
	v_fma_f32 v172, v172, v170, v190
	v_fma_f32 v175, v175, v173, v190
	v_fma_f32 v178, v178, v176, v190
	v_fma_f32 v166, v166, v164, v191
	v_fma_f32 v169, v169, v167, v191
	v_fma_f32 v172, v172, v170, v191
	v_fma_f32 v175, v175, v173, v191
	v_fma_f32 v178, v178, v176, v191
	v_mul_f32_e32 v166, v166, v164
	v_mul_f32_e32 v169, v169, v167
	v_mul_f32_e32 v172, v172, v170
	v_mul_f32_e32 v175, v175, v173
	v_mul_f32_e32 v178, v178, v176
	v_mul_f32_e32 v166, v166, v165
	v_mul_f32_e32 v169, v169, v168
	v_mul_f32_e32 v172, v172, v171
	v_mul_f32_e32 v175, v175, v174
	v_mul_f32_e32 v178, v178, v177
	v_mul_f32_e32 v166, v138, v166
	v_mul_f32_e32 v169, v139, v169
	v_mul_f32_e32 v172, v134, v172
	v_mul_f32_e32 v175, v135, v175
	v_mul_f32_e32 v178, v144, v178
	v_sub_f32_e32 v165, v138, v166
	v_sub_f32_e32 v168, v139, v169
	v_sub_f32_e32 v171, v134, v172
	v_sub_f32_e32 v174, v135, v175
	v_sub_f32_e32 v177, v144, v178
	v_cmp_gt_f32_e64 s[100:101], 0, v138
	s_nop 1
	v_cndmask_b32_e64 v138, v165, v166, s[100:101]
	v_cmp_gt_f32_e64 s[100:101], 0, v139
	s_nop 1
	v_cndmask_b32_e64 v139, v168, v169, s[100:101]
	v_cmp_gt_f32_e64 s[100:101], 0, v134
	s_nop 1
	v_cndmask_b32_e64 v134, v171, v172, s[100:101]
	v_cmp_gt_f32_e64 s[100:101], 0, v135
	s_nop 1
	v_cndmask_b32_e64 v135, v174, v175, s[100:101]
	v_cmp_gt_f32_e64 s[100:101], 0, v144
	s_nop 1
	v_cndmask_b32_e64 v144, v177, v178, s[100:101]
	s_mov_b32 s0, 0x48000
	v_and_b32_e32 v164, 0x7fffffff, v145
	v_and_b32_e32 v167, 0x7fffffff, v140
	v_and_b32_e32 v170, 0x7fffffff, v141
	v_mul_f32_e32 v165, v145, v145
	v_mul_f32_e32 v168, v140, v140
	v_mul_f32_e32 v171, v141, v141
	v_fma_f32 v164, v164, s14, 1.0
; __device__ __forceinline__ unsigned cvt_pk_bf16(float lo, float hi) { const f32x2 v = {lo, hi}; const bf16v2_t b = __builtin_convertvector(v, bf16v2_t); return __builtin_bit_cast(unsigned, b); }
; __device__ __forceinline__ float sigmoidf_(float x) { return __builtin_amdgcn_rcpf(1.0f + __builtin_amdgcn_exp2f(x * -1.44269504089f)); }
; __device__ __forceinline__ float siluf_(float x) { return x * __builtin_amdgcn_rcpf(1.0f + __builtin_amdgcn_exp2f(x * -1.44269504089f)); }
; __device__ __forceinline__ f32x2 gelu_pk(f32x2 v) {
;     const f32x2 av = __builtin_elementwise_abs(v), d = av * 0.2316418882f + 1.0f;
;     f32x2 t; t.x = __builtin_amdgcn_rcpf(d.x); t.y = __builtin_amdgcn_rcpf(d.y);
;     f32x2 q = t * 0.5307027145f + (-0.7265760135f); q = q * t + 0.7107068705f; q = q * t + (-0.142248368f); q = q * t + 0.127414796f; q = q * t;
;     const f32x2 s = (v * v) * (-0.72134752044f);
;     f32x2 e; e.x = __builtin_amdgcn_exp2f(s.x); e.y = __builtin_amdgcn_exp2f(s.y);
;     const f32x2 m = v * (q * e), r = v - m;
;     f32x2 o; o.x = v.x < 0.f ? m.x : r.x; o.y = v.y < 0.f ? m.y : r.y; return o;
;     __device__ __forceinline__ void epi_proj(const f32x4 (&acc)[2][2][4][2], const pg8::Unit& u, int wr, int wc, int fr, int fq) const {
;     ...
;                             f32x4 v0 = acc[ai][bj][m][0] * rstd, v1 = acc[ai][bj][m][1] * rstd;
;                             if (slot < 2) {
;                                 f32x2 a = gelu_pk((f32x2){v0[0], v0[1]}), b = gelu_pk((f32x2){v0[2], v0[3]}), c = gelu_pk((f32x2){v1[0], v1[1]}), d = gelu_pk((f32x2){v1[2], v1[3]});
;                                 v0 = (f32x4){a.x, a.y, b.x, b.y}; v1 = (f32x4){c.x, c.y, d.x, d.y};
;                             } else if (slot == 5) {
; #pragma unroll
;                                 for (int j = 0; j < 4; ++j) { v0[j] = siluf_(v0[j]); v1[j] = siluf_(v1[j]); }
;                             } else if (slot >= 6) {
; #pragma unroll
;                                 for (int j = 0; j < 4; ++j) { v0[j] = sigmoidf_(v0[j]); v1[j] = sigmoidf_(v1[j]); }
;                             }
;                             u32x4 w; w.x = cvt_pk_bf16(v0[0], v0[1]); w.y = cvt_pk_bf16(v0[2], v0[3]); w.z = cvt_pk_bf16(v1[0], v1[1]); w.w = cvt_pk_bf16(v1[2], v1[3]);
;                             *(u32x4*)(rowp + bj * 128) = w;
	v_fma_f32 v167, v167, s14, 1.0
	v_fma_f32 v170, v170, s14, 1.0
	v_mul_f32_e32 v165, s20, v165
	v_mul_f32_e32 v168, s20, v168
	v_mul_f32_e32 v171, s20, v171
	v_rcp_f32_e32 v164, v164
	v_rcp_f32_e32 v167, v167
	v_rcp_f32_e32 v170, v170
	s_nop 0
	v_exp_f32_e32 v165, v165
	v_exp_f32_e32 v168, v168
	v_exp_f32_e32 v171, v171
	s_nop 0
	v_fma_f32 v166, v164, s15, v188
	v_fma_f32 v169, v167, s15, v188
	v_fma_f32 v172, v170, s15, v188
	v_fma_f32 v166, v166, v164, v189
	v_fma_f32 v169, v169, v167, v189
	v_fma_f32 v172, v172, v170, v189
	v_fma_f32 v166, v166, v164, v190
	v_fma_f32 v169, v169, v167, v190
	v_fma_f32 v172, v172, v170, v190
	v_fma_f32 v166, v166, v164, v191
	v_fma_f32 v169, v169, v167, v191
	v_fma_f32 v172, v172, v170, v191
	v_mul_f32_e32 v166, v166, v164
	v_mul_f32_e32 v169, v169, v167
	v_mul_f32_e32 v172, v172, v170
	v_mul_f32_e32 v166, v166, v165
	v_mul_f32_e32 v169, v169, v168
	v_mul_f32_e32 v172, v172, v171
	v_mul_f32_e32 v166, v145, v166
	v_mul_f32_e32 v169, v140, v169
	v_mul_f32_e32 v172, v141, v172
	v_sub_f32_e32 v165, v145, v166
	v_sub_f32_e32 v168, v140, v169
	v_sub_f32_e32 v171, v141, v172
	v_cmp_gt_f32_e64 s[100:101], 0, v145
	s_nop 1
	v_cndmask_b32_e64 v145, v165, v166, s[100:101]
	v_cmp_gt_f32_e64 s[100:101], 0, v140
	s_nop 1
	v_cndmask_b32_e64 v140, v168, v169, s[100:101]
	v_cmp_gt_f32_e64 s[100:101], 0, v141
	s_nop 1
	v_cndmask_b32_e64 v141, v171, v172, s[100:101]
	v_mov_b32_e32 v146, v140
	v_mov_b32_e32 v147, v141
	v_cvt_pk_bf16_f32 v138, v138, v139
	v_cvt_pk_bf16_f32 v139, v134, v135
	v_add_co_u32_e32 v134, vcc, s0, v136
	v_cvt_pk_bf16_f32 v140, v144, v145
	v_cvt_pk_bf16_f32 v141, v146, v147
	v_addc_co_u32_e32 v135, vcc, 0, v137, vcc
	global_store_dwordx4 v[134:135], v[138:141], off
	v_pk_mul_f32 v[134:135], v[46:47], v[132:133] op_sel_hi:[1,0]
	s_mov_b64 s[0:1], 0x50000
	v_pk_mul_f32 v[138:139], v[44:45], v[132:133] op_sel_hi:[1,0]
	v_pk_mul_f32 v[140:141], v[42:43], v[132:133] op_sel_hi:[1,0]
	v_pk_mul_f32 v[132:133], v[40:41], v[132:133] op_sel_hi:[1,0]
	v_and_b32_e32 v164, 0x7fffffff, v138
	v_and_b32_e32 v167, 0x7fffffff, v132
	v_and_b32_e32 v170, 0x7fffffff, v133
	v_and_b32_e32 v173, 0x7fffffff, v139
	v_mul_f32_e32 v165, v138, v138
	v_mul_f32_e32 v168, v132, v132
	v_mul_f32_e32 v171, v133, v133
	v_mul_f32_e32 v174, v139, v139
	v_fma_f32 v164, v164, s14, 1.0
	v_fma_f32 v167, v167, s14, 1.0
	v_fma_f32 v170, v170, s14, 1.0
	v_fma_f32 v173, v173, s14, 1.0
	v_mul_f32_e32 v165, s20, v165
	v_mul_f32_e32 v168, s20, v168
	v_mul_f32_e32 v171, s20, v171
	v_mul_f32_e32 v174, s20, v174
	v_rcp_f32_e32 v164, v164
	v_rcp_f32_e32 v167, v167
	v_rcp_f32_e32 v170, v170
	v_rcp_f32_e32 v173, v173
	s_nop 0
	v_exp_f32_e32 v165, v165
	v_exp_f32_e32 v168, v168
	v_exp_f32_e32 v171, v171
	v_exp_f32_e32 v174, v174
	s_nop 0
	v_fma_f32 v166, v164, s15, v188
	v_fma_f32 v169, v167, s15, v188
	v_fma_f32 v172, v170, s15, v188
	v_fma_f32 v175, v173, s15, v188
	v_fma_f32 v166, v166, v164, v189
	v_fma_f32 v169, v169, v167, v189
	v_fma_f32 v172, v172, v170, v189
	v_fma_f32 v175, v175, v173, v189
	v_fma_f32 v166, v166, v164, v190
	v_fma_f32 v169, v169, v167, v190
	v_fma_f32 v172, v172, v170, v190
	v_fma_f32 v175, v175, v173, v190
	v_fma_f32 v166, v166, v164, v191
	v_fma_f32 v169, v169, v167, v191
	v_fma_f32 v172, v172, v170, v191
	v_fma_f32 v175, v175, v173, v191
	v_mul_f32_e32 v166, v166, v164
	v_mul_f32_e32 v169, v169, v167
	v_mul_f32_e32 v172, v172, v170
	v_mul_f32_e32 v175, v175, v173
	v_mul_f32_e32 v166, v166, v165
	v_mul_f32_e32 v169, v169, v168
	v_mul_f32_e32 v172, v172, v171
	v_mul_f32_e32 v175, v175, v174
	v_mul_f32_e32 v166, v138, v166
	v_mul_f32_e32 v169, v132, v169
	v_mul_f32_e32 v172, v133, v172
	v_mul_f32_e32 v175, v139, v175
	v_sub_f32_e32 v165, v138, v166
	v_sub_f32_e32 v168, v132, v169
	v_sub_f32_e32 v171, v133, v172
	v_sub_f32_e32 v174, v139, v175
	v_cmp_gt_f32_e64 s[100:101], 0, v138
	s_nop 1
	v_cndmask_b32_e64 v138, v165, v166, s[100:101]
	v_cmp_gt_f32_e64 s[100:101], 0, v132
	s_nop 1
	v_cndmask_b32_e64 v132, v168, v169, s[100:101]
	v_cmp_gt_f32_e64 s[100:101], 0, v133
	s_nop 1
	v_cndmask_b32_e64 v133, v171, v172, s[100:101]
	v_cmp_gt_f32_e64 s[100:101], 0, v139
	s_nop 1
	v_cndmask_b32_e64 v139, v174, v175, s[100:101]
	v_mov_b32_e32 v144, v132
	v_mov_b32_e32 v145, v133
	v_and_b32_e32 v164, 0x7fffffff, v134
	v_mul_f32_e32 v165, v134, v134
	v_fma_f32 v164, v164, s14, 1.0
	v_mul_f32_e32 v165, s20, v165
	v_rcp_f32_e32 v164, v164
	s_nop 0
	v_exp_f32_e32 v165, v165
	s_nop 0
	v_fma_f32 v166, v164, s15, v188
	v_fma_f32 v166, v166, v164, v189
	v_fma_f32 v166, v166, v164, v190
	v_fma_f32 v166, v166, v164, v191
	v_mul_f32_e32 v166, v166, v164
	v_mul_f32_e32 v166, v166, v165
	v_mul_f32_e32 v166, v134, v166
	v_sub_f32_e32 v165, v134, v166
	v_cmp_gt_f32_e64 s[100:101], 0, v134
	s_nop 1
	v_cndmask_b32_e64 v132, v165, v166, s[100:101]
	v_and_b32_e32 v164, 0x7fffffff, v140
	v_and_b32_e32 v167, 0x7fffffff, v135
	v_mul_f32_e32 v165, v140, v140
	v_mul_f32_e32 v168, v135, v135
	v_fma_f32 v164, v164, s14, 1.0
	v_fma_f32 v167, v167, s14, 1.0
	v_mul_f32_e32 v165, s20, v165
	v_mul_f32_e32 v168, s20, v168
	v_rcp_f32_e32 v164, v164
	v_rcp_f32_e32 v167, v167
	s_nop 0
	v_exp_f32_e32 v165, v165
	v_exp_f32_e32 v168, v168
	s_nop 0
	v_fma_f32 v166, v164, s15, v188
	v_fma_f32 v169, v167, s15, v188
	v_fma_f32 v166, v166, v164, v189
	v_fma_f32 v169, v169, v167, v189
	v_fma_f32 v166, v166, v164, v190
	v_fma_f32 v169, v169, v167, v190
	v_fma_f32 v166, v166, v164, v191
	v_fma_f32 v169, v169, v167, v191
	v_mul_f32_e32 v166, v166, v164
	v_mul_f32_e32 v169, v169, v167
	v_mul_f32_e32 v166, v166, v165
	v_mul_f32_e32 v169, v169, v168
	v_mul_f32_e32 v166, v140, v166
; __device__ __forceinline__ unsigned cvt_pk_bf16(float lo, float hi) { const f32x2 v = {lo, hi}; const bf16v2_t b = __builtin_convertvector(v, bf16v2_t); return __builtin_bit_cast(unsigned, b); }
; __device__ __forceinline__ float sigmoidf_(float x) { return __builtin_amdgcn_rcpf(1.0f + __builtin_amdgcn_exp2f(x * -1.44269504089f)); }
; __device__ __forceinline__ float siluf_(float x) { return x * __builtin_amdgcn_rcpf(1.0f + __builtin_amdgcn_exp2f(x * -1.44269504089f)); }
; __device__ __forceinline__ f32x2 gelu_pk(f32x2 v) {
;     const f32x2 av = __builtin_elementwise_abs(v), d = av * 0.2316418882f + 1.0f;
;     f32x2 t; t.x = __builtin_amdgcn_rcpf(d.x); t.y = __builtin_amdgcn_rcpf(d.y);
;     f32x2 q = t * 0.5307027145f + (-0.7265760135f); q = q * t + 0.7107068705f; q = q * t + (-0.142248368f); q = q * t + 0.127414796f; q = q * t;
;     const f32x2 s = (v * v) * (-0.72134752044f);
;     f32x2 e; e.x = __builtin_amdgcn_exp2f(s.x); e.y = __builtin_amdgcn_exp2f(s.y);
;     const f32x2 m = v * (q * e), r = v - m;
;     f32x2 o; o.x = v.x < 0.f ? m.x : r.x; o.y = v.y < 0.f ? m.y : r.y; return o;
;     __device__ __forceinline__ void epi_proj(const f32x4 (&acc)[2][2][4][2], const pg8::Unit& u, int wr, int wc, int fr, int fq) const {
;     ...
;                             f32x4 v0 = acc[ai][bj][m][0] * rstd, v1 = acc[ai][bj][m][1] * rstd;
;                             if (slot < 2) {
;                                 f32x2 a = gelu_pk((f32x2){v0[0], v0[1]}), b = gelu_pk((f32x2){v0[2], v0[3]}), c = gelu_pk((f32x2){v1[0], v1[1]}), d = gelu_pk((f32x2){v1[2], v1[3]});
;                                 v0 = (f32x4){a.x, a.y, b.x, b.y}; v1 = (f32x4){c.x, c.y, d.x, d.y};
;                             } else if (slot == 5) {
; #pragma unroll
;                                 for (int j = 0; j < 4; ++j) { v0[j] = siluf_(v0[j]); v1[j] = siluf_(v1[j]); }
;                             } else if (slot >= 6) {
; #pragma unroll
;                                 for (int j = 0; j < 4; ++j) { v0[j] = sigmoidf_(v0[j]); v1[j] = sigmoidf_(v1[j]); }
;                             }
;                             u32x4 w; w.x = cvt_pk_bf16(v0[0], v0[1]); w.y = cvt_pk_bf16(v0[2], v0[3]); w.z = cvt_pk_bf16(v1[0], v1[1]); w.w = cvt_pk_bf16(v1[2], v1[3]);
;                             *(u32x4*)(rowp + bj * 128) = w;
	v_mul_f32_e32 v169, v135, v169
	v_sub_f32_e32 v165, v140, v166
	v_sub_f32_e32 v168, v135, v169
	v_cmp_gt_f32_e64 s[100:101], 0, v140
	s_nop 1
	v_cndmask_b32_e64 v134, v165, v166, s[100:101]
	v_cmp_gt_f32_e64 s[100:101], 0, v135
	s_nop 1
	v_cndmask_b32_e64 v133, v168, v169, s[100:101]
	v_mov_b32_e32 v146, v132
	v_mov_b32_e32 v147, v133
	v_and_b32_e32 v164, 0x7fffffff, v141
	v_mul_f32_e32 v165, v141, v141
	v_fma_f32 v164, v164, s14, 1.0
	v_mul_f32_e32 v165, s20, v165
	v_rcp_f32_e32 v164, v164
	s_nop 0
	v_exp_f32_e32 v165, v165
	s_nop 0
	v_fma_f32 v166, v164, s15, v188
	v_fma_f32 v166, v166, v164, v189
	v_fma_f32 v166, v166, v164, v190
	v_fma_f32 v166, v166, v164, v191
	v_mul_f32_e32 v166, v166, v164
	v_mul_f32_e32 v166, v166, v165
	v_mul_f32_e32 v166, v141, v166
	v_sub_f32_e32 v165, v141, v166
	v_cmp_gt_f32_e64 s[100:101], 0, v141
	s_nop 1
	v_cndmask_b32_e64 v135, v165, v166, s[100:101]
	v_mov_b32_e32 v140, v134
	v_mov_b32_e32 v141, v135
	v_cvt_pk_bf16_f32 v132, v138, v139
	v_cvt_pk_bf16_f32 v133, v146, v147
	v_cvt_pk_bf16_f32 v134, v144, v145
	v_cvt_pk_bf16_f32 v135, v140, v141
	global_store_dwordx4 v[142:143], v[132:135], off offset:256
	v_pk_mul_f32 v[140:141], v[18:19], v[130:131] op_sel_hi:[1,0]
	v_pk_mul_f32 v[142:143], v[16:17], v[130:131] op_sel_hi:[1,0]
	v_pk_mul_f32 v[134:135], v[20:21], v[130:131] op_sel_hi:[1,0]
	v_pk_mul_f32 v[132:133], v[22:23], v[130:131] op_sel_hi:[1,0]
	v_lshl_add_u64 v[138:139], v[136:137], 0, s[0:1]
	v_and_b32_e32 v164, 0x7fffffff, v134
	v_and_b32_e32 v167, 0x7fffffff, v135
	v_and_b32_e32 v170, 0x7fffffff, v140
	v_and_b32_e32 v173, 0x7fffffff, v141
	v_and_b32_e32 v176, 0x7fffffff, v142
	v_mul_f32_e32 v165, v134, v134
	v_mul_f32_e32 v168, v135, v135
	v_mul_f32_e32 v171, v140, v140
	v_mul_f32_e32 v174, v141, v141
	v_mul_f32_e32 v177, v142, v142
	v_fma_f32 v164, v164, s14, 1.0
	v_fma_f32 v167, v167, s14, 1.0
	v_fma_f32 v170, v170, s14, 1.0
	v_fma_f32 v173, v173, s14, 1.0
	v_fma_f32 v176, v176, s14, 1.0
	v_mul_f32_e32 v165, s20, v165
	v_mul_f32_e32 v168, s20, v168
	v_mul_f32_e32 v171, s20, v171
	v_mul_f32_e32 v174, s20, v174
	v_mul_f32_e32 v177, s20, v177
	v_rcp_f32_e32 v164, v164
	v_rcp_f32_e32 v167, v167
	v_rcp_f32_e32 v170, v170
	v_rcp_f32_e32 v173, v173
	v_rcp_f32_e32 v176, v176
	s_nop 0
	v_exp_f32_e32 v165, v165
	v_exp_f32_e32 v168, v168
	v_exp_f32_e32 v171, v171
	v_exp_f32_e32 v174, v174
	v_exp_f32_e32 v177, v177
	s_nop 0
	v_fma_f32 v166, v164, s15, v188
	v_fma_f32 v169, v167, s15, v188
	v_fma_f32 v172, v170, s15, v188
	v_fma_f32 v175, v173, s15, v188
	v_fma_f32 v178, v176, s15, v188
	v_fma_f32 v166, v166, v164, v189
	v_fma_f32 v169, v169, v167, v189
	v_fma_f32 v172, v172, v170, v189
	v_fma_f32 v175, v175, v173, v189
	v_fma_f32 v178, v178, v176, v189
	v_fma_f32 v166, v166, v164, v190
	v_fma_f32 v169, v169, v167, v190
	v_fma_f32 v172, v172, v170, v190
	v_fma_f32 v175, v175, v173, v190
	v_fma_f32 v178, v178, v176, v190
	v_fma_f32 v166, v166, v164, v191
	v_fma_f32 v169, v169, v167, v191
	v_fma_f32 v172, v172, v170, v191
	v_fma_f32 v175, v175, v173, v191
	v_fma_f32 v178, v178, v176, v191
	v_mul_f32_e32 v166, v166, v164
	v_mul_f32_e32 v169, v169, v167
	v_mul_f32_e32 v172, v172, v170
	v_mul_f32_e32 v175, v175, v173
	v_mul_f32_e32 v178, v178, v176
	v_mul_f32_e32 v166, v166, v165
	v_mul_f32_e32 v169, v169, v168
	v_mul_f32_e32 v172, v172, v171
	v_mul_f32_e32 v175, v175, v174
	v_mul_f32_e32 v178, v178, v177
	v_mul_f32_e32 v166, v134, v166
	v_mul_f32_e32 v169, v135, v169
	v_mul_f32_e32 v172, v140, v172
	v_mul_f32_e32 v175, v141, v175
	v_mul_f32_e32 v178, v142, v178
	v_sub_f32_e32 v165, v134, v166
	v_sub_f32_e32 v168, v135, v169
	v_sub_f32_e32 v171, v140, v172
	v_sub_f32_e32 v174, v141, v175
	v_sub_f32_e32 v177, v142, v178
	v_cmp_gt_f32_e64 s[100:101], 0, v134
	s_nop 1
	v_cndmask_b32_e64 v134, v165, v166, s[100:101]
	v_cmp_gt_f32_e64 s[100:101], 0, v135
	s_nop 1
	v_cndmask_b32_e64 v135, v168, v169, s[100:101]
	v_cmp_gt_f32_e64 s[100:101], 0, v140
	s_nop 1
	v_cndmask_b32_e64 v140, v171, v172, s[100:101]
	v_cmp_gt_f32_e64 s[100:101], 0, v141
	s_nop 1
	v_cndmask_b32_e64 v141, v174, v175, s[100:101]
	v_cmp_gt_f32_e64 s[100:101], 0, v142
	s_nop 1
	v_cndmask_b32_e64 v142, v177, v178, s[100:101]
	s_mov_b32 s0, 0x50000
	v_and_b32_e32 v164, 0x7fffffff, v143
	v_and_b32_e32 v167, 0x7fffffff, v132
	v_and_b32_e32 v170, 0x7fffffff, v133
	v_mul_f32_e32 v165, v143, v143
	v_mul_f32_e32 v168, v132, v132
	v_mul_f32_e32 v171, v133, v133
	v_fma_f32 v164, v164, s14, 1.0
	v_fma_f32 v167, v167, s14, 1.0
	v_fma_f32 v170, v170, s14, 1.0
	v_mul_f32_e32 v165, s20, v165
	v_mul_f32_e32 v168, s20, v168
	v_mul_f32_e32 v171, s20, v171
	v_rcp_f32_e32 v164, v164
	v_rcp_f32_e32 v167, v167
	v_rcp_f32_e32 v170, v170
	s_nop 0
	v_exp_f32_e32 v165, v165
	v_exp_f32_e32 v168, v168
	v_exp_f32_e32 v171, v171
	s_nop 0
	v_fma_f32 v166, v164, s15, v188
	v_fma_f32 v169, v167, s15, v188
	v_fma_f32 v172, v170, s15, v188
	v_fma_f32 v166, v166, v164, v189
	v_fma_f32 v169, v169, v167, v189
	v_fma_f32 v172, v172, v170, v189
	v_fma_f32 v166, v166, v164, v190
	v_fma_f32 v169, v169, v167, v190
	v_fma_f32 v172, v172, v170, v190
	v_fma_f32 v166, v166, v164, v191
	v_fma_f32 v169, v169, v167, v191
	v_fma_f32 v172, v172, v170, v191
	v_mul_f32_e32 v166, v166, v164
	v_mul_f32_e32 v169, v169, v167
	v_mul_f32_e32 v172, v172, v170
	v_mul_f32_e32 v166, v166, v165
	v_mul_f32_e32 v169, v169, v168
	v_mul_f32_e32 v172, v172, v171
	v_mul_f32_e32 v166, v143, v166
	v_mul_f32_e32 v169, v132, v169
	v_mul_f32_e32 v172, v133, v172
	v_sub_f32_e32 v165, v143, v166
	v_sub_f32_e32 v168, v132, v169
	v_sub_f32_e32 v171, v133, v172
	v_cmp_gt_f32_e64 s[100:101], 0, v143
	s_nop 1
; __device__ __forceinline__ unsigned cvt_pk_bf16(float lo, float hi) { const f32x2 v = {lo, hi}; const bf16v2_t b = __builtin_convertvector(v, bf16v2_t); return __builtin_bit_cast(unsigned, b); }
; __device__ __forceinline__ float sigmoidf_(float x) { return __builtin_amdgcn_rcpf(1.0f + __builtin_amdgcn_exp2f(x * -1.44269504089f)); }
; __device__ __forceinline__ float siluf_(float x) { return x * __builtin_amdgcn_rcpf(1.0f + __builtin_amdgcn_exp2f(x * -1.44269504089f)); }
; __device__ __forceinline__ f32x2 gelu_pk(f32x2 v) {
;     const f32x2 av = __builtin_elementwise_abs(v), d = av * 0.2316418882f + 1.0f;
;     f32x2 t; t.x = __builtin_amdgcn_rcpf(d.x); t.y = __builtin_amdgcn_rcpf(d.y);
;     f32x2 q = t * 0.5307027145f + (-0.7265760135f); q = q * t + 0.7107068705f; q = q * t + (-0.142248368f); q = q * t + 0.127414796f; q = q * t;
;     const f32x2 s = (v * v) * (-0.72134752044f);
;     f32x2 e; e.x = __builtin_amdgcn_exp2f(s.x); e.y = __builtin_amdgcn_exp2f(s.y);
;     const f32x2 m = v * (q * e), r = v - m;
;     f32x2 o; o.x = v.x < 0.f ? m.x : r.x; o.y = v.y < 0.f ? m.y : r.y; return o;
;     __device__ __forceinline__ void epi_proj(const f32x4 (&acc)[2][2][4][2], const pg8::Unit& u, int wr, int wc, int fr, int fq) const {
;     ...
;                             f32x4 v0 = acc[ai][bj][m][0] * rstd, v1 = acc[ai][bj][m][1] * rstd;
;                             if (slot < 2) {
;                                 f32x2 a = gelu_pk((f32x2){v0[0], v0[1]}), b = gelu_pk((f32x2){v0[2], v0[3]}), c = gelu_pk((f32x2){v1[0], v1[1]}), d = gelu_pk((f32x2){v1[2], v1[3]});
;                                 v0 = (f32x4){a.x, a.y, b.x, b.y}; v1 = (f32x4){c.x, c.y, d.x, d.y};
;                             } else if (slot == 5) {
; #pragma unroll
;                                 for (int j = 0; j < 4; ++j) { v0[j] = siluf_(v0[j]); v1[j] = siluf_(v1[j]); }
;                             } else if (slot >= 6) {
; #pragma unroll
;                                 for (int j = 0; j < 4; ++j) { v0[j] = sigmoidf_(v0[j]); v1[j] = sigmoidf_(v1[j]); }
;                             }
;                             u32x4 w; w.x = cvt_pk_bf16(v0[0], v0[1]); w.y = cvt_pk_bf16(v0[2], v0[3]); w.z = cvt_pk_bf16(v1[0], v1[1]); w.w = cvt_pk_bf16(v1[2], v1[3]);
;                             *(u32x4*)(rowp + bj * 128) = w;
	v_cndmask_b32_e64 v143, v165, v166, s[100:101]
	v_cmp_gt_f32_e64 s[100:101], 0, v132
	s_nop 1
	v_cndmask_b32_e64 v132, v168, v169, s[100:101]
	v_cmp_gt_f32_e64 s[100:101], 0, v133
	s_nop 1
	v_cndmask_b32_e64 v133, v171, v172, s[100:101]
	v_mov_b32_e32 v144, v132
	v_mov_b32_e32 v145, v133
	v_cvt_pk_bf16_f32 v132, v134, v135
	v_cvt_pk_bf16_f32 v135, v140, v141
	v_add_co_u32_e32 v140, vcc, s0, v136
	v_cvt_pk_bf16_f32 v133, v144, v145
	v_cvt_pk_bf16_f32 v134, v142, v143
	v_addc_co_u32_e32 v141, vcc, 0, v137, vcc
	global_store_dwordx4 v[140:141], v[132:135], off
	v_pk_mul_f32 v[140:141], v[26:27], v[130:131] op_sel_hi:[1,0]
	s_mov_b64 s[0:1], 0x58000
	v_pk_mul_f32 v[132:133], v[30:31], v[130:131] op_sel_hi:[1,0]
	v_pk_mul_f32 v[134:135], v[28:29], v[130:131] op_sel_hi:[1,0]
	v_pk_mul_f32 v[130:131], v[24:25], v[130:131] op_sel_hi:[1,0]
	v_and_b32_e32 v164, 0x7fffffff, v134
	v_and_b32_e32 v167, 0x7fffffff, v130
	v_and_b32_e32 v170, 0x7fffffff, v131
	v_and_b32_e32 v173, 0x7fffffff, v135
	v_mul_f32_e32 v165, v134, v134
	v_mul_f32_e32 v168, v130, v130
	v_mul_f32_e32 v171, v131, v131
	v_mul_f32_e32 v174, v135, v135
	v_fma_f32 v164, v164, s14, 1.0
	v_fma_f32 v167, v167, s14, 1.0
	v_fma_f32 v170, v170, s14, 1.0
	v_fma_f32 v173, v173, s14, 1.0
	v_mul_f32_e32 v165, s20, v165
	v_mul_f32_e32 v168, s20, v168
	v_mul_f32_e32 v171, s20, v171
	v_mul_f32_e32 v174, s20, v174
	v_rcp_f32_e32 v164, v164
	v_rcp_f32_e32 v167, v167
	v_rcp_f32_e32 v170, v170
	v_rcp_f32_e32 v173, v173
	s_nop 0
	v_exp_f32_e32 v165, v165
	v_exp_f32_e32 v168, v168
	v_exp_f32_e32 v171, v171
	v_exp_f32_e32 v174, v174
	s_nop 0
	v_fma_f32 v166, v164, s15, v188
	v_fma_f32 v169, v167, s15, v188
	v_fma_f32 v172, v170, s15, v188
	v_fma_f32 v175, v173, s15, v188
	v_fma_f32 v166, v166, v164, v189
	v_fma_f32 v169, v169, v167, v189
	v_fma_f32 v172, v172, v170, v189
	v_fma_f32 v175, v175, v173, v189
	v_fma_f32 v166, v166, v164, v190
	v_fma_f32 v169, v169, v167, v190
	v_fma_f32 v172, v172, v170, v190
	v_fma_f32 v175, v175, v173, v190
	v_fma_f32 v166, v166, v164, v191
	v_fma_f32 v169, v169, v167, v191
	v_fma_f32 v172, v172, v170, v191
	v_fma_f32 v175, v175, v173, v191
	v_mul_f32_e32 v166, v166, v164
	v_mul_f32_e32 v169, v169, v167
	v_mul_f32_e32 v172, v172, v170
	v_mul_f32_e32 v175, v175, v173
	v_mul_f32_e32 v166, v166, v165
	v_mul_f32_e32 v169, v169, v168
	v_mul_f32_e32 v172, v172, v171
	v_mul_f32_e32 v175, v175, v174
	v_mul_f32_e32 v166, v134, v166
	v_mul_f32_e32 v169, v130, v169
	v_mul_f32_e32 v172, v131, v172
	v_mul_f32_e32 v175, v135, v175
	v_sub_f32_e32 v165, v134, v166
	v_sub_f32_e32 v168, v130, v169
	v_sub_f32_e32 v171, v131, v172
	v_sub_f32_e32 v174, v135, v175
	v_cmp_gt_f32_e64 s[100:101], 0, v134
	s_nop 1
	v_cndmask_b32_e64 v134, v165, v166, s[100:101]
	v_cmp_gt_f32_e64 s[100:101], 0, v130
	s_nop 1
	v_cndmask_b32_e64 v130, v168, v169, s[100:101]
	v_cmp_gt_f32_e64 s[100:101], 0, v131
	s_nop 1
	v_cndmask_b32_e64 v131, v171, v172, s[100:101]
	v_cmp_gt_f32_e64 s[100:101], 0, v135
	s_nop 1
	v_cndmask_b32_e64 v135, v174, v175, s[100:101]
	v_mov_b32_e32 v142, v130
	v_mov_b32_e32 v143, v131
	v_and_b32_e32 v164, 0x7fffffff, v132
	v_mul_f32_e32 v165, v132, v132
	v_fma_f32 v164, v164, s14, 1.0
	v_mul_f32_e32 v165, s20, v165
	v_rcp_f32_e32 v164, v164
	s_nop 0
	v_exp_f32_e32 v165, v165
	s_nop 0
	v_fma_f32 v166, v164, s15, v188
	v_fma_f32 v166, v166, v164, v189
	v_fma_f32 v166, v166, v164, v190
	v_fma_f32 v166, v166, v164, v191
	v_mul_f32_e32 v166, v166, v164
	v_mul_f32_e32 v166, v166, v165
	v_mul_f32_e32 v166, v132, v166
	v_sub_f32_e32 v165, v132, v166
	v_cmp_gt_f32_e64 s[100:101], 0, v132
	s_nop 1
	v_cndmask_b32_e64 v130, v165, v166, s[100:101]
	v_and_b32_e32 v164, 0x7fffffff, v140
	v_and_b32_e32 v167, 0x7fffffff, v133
	v_mul_f32_e32 v165, v140, v140
	v_mul_f32_e32 v168, v133, v133
	v_fma_f32 v164, v164, s14, 1.0
	v_fma_f32 v167, v167, s14, 1.0
	v_mul_f32_e32 v165, s20, v165
	v_mul_f32_e32 v168, s20, v168
	v_rcp_f32_e32 v164, v164
	v_rcp_f32_e32 v167, v167
	s_nop 0
	v_exp_f32_e32 v165, v165
	v_exp_f32_e32 v168, v168
	s_nop 0
	v_fma_f32 v166, v164, s15, v188
	v_fma_f32 v169, v167, s15, v188
	v_fma_f32 v166, v166, v164, v189
	v_fma_f32 v169, v169, v167, v189
	v_fma_f32 v166, v166, v164, v190
	v_fma_f32 v169, v169, v167, v190
	v_fma_f32 v166, v166, v164, v191
	v_fma_f32 v169, v169, v167, v191
	v_mul_f32_e32 v166, v166, v164
	v_mul_f32_e32 v169, v169, v167
	v_mul_f32_e32 v166, v166, v165
	v_mul_f32_e32 v169, v169, v168
	v_mul_f32_e32 v166, v140, v166
	v_mul_f32_e32 v169, v133, v169
	v_sub_f32_e32 v165, v140, v166
	v_sub_f32_e32 v168, v133, v169
	v_cmp_gt_f32_e64 s[100:101], 0, v140
	s_nop 1
	v_cndmask_b32_e64 v132, v165, v166, s[100:101]
	v_cmp_gt_f32_e64 s[100:101], 0, v133
	s_nop 1
	v_cndmask_b32_e64 v131, v168, v169, s[100:101]
	v_mov_b32_e32 v144, v130
	v_mov_b32_e32 v145, v131
	v_and_b32_e32 v164, 0x7fffffff, v141
	v_mul_f32_e32 v165, v141, v141
	v_fma_f32 v164, v164, s14, 1.0
	v_mul_f32_e32 v165, s20, v165
	v_rcp_f32_e32 v164, v164
	s_nop 0
	v_exp_f32_e32 v165, v165
	s_nop 0
	v_fma_f32 v166, v164, s15, v188
	v_fma_f32 v166, v166, v164, v189
	v_fma_f32 v166, v166, v164, v190
	v_fma_f32 v166, v166, v164, v191
	v_mul_f32_e32 v166, v166, v164
	v_mul_f32_e32 v166, v166, v165
	v_mul_f32_e32 v166, v141, v166
	v_sub_f32_e32 v165, v141, v166
	v_cmp_gt_f32_e64 s[100:101], 0, v141
	s_nop 1
	v_cndmask_b32_e64 v133, v165, v166, s[100:101]
	v_mov_b32_e32 v140, v132
	v_mov_b32_e32 v141, v133
	v_cvt_pk_bf16_f32 v130, v134, v135
	v_cvt_pk_bf16_f32 v131, v144, v145
	v_cvt_pk_bf16_f32 v132, v142, v143
	v_cvt_pk_bf16_f32 v133, v140, v141
	global_store_dwordx4 v[138:139], v[130:133], off offset:256
; __device__ __forceinline__ unsigned cvt_pk_bf16(float lo, float hi) { const f32x2 v = {lo, hi}; const bf16v2_t b = __builtin_convertvector(v, bf16v2_t); return __builtin_bit_cast(unsigned, b); }
; __device__ __forceinline__ float sigmoidf_(float x) { return __builtin_amdgcn_rcpf(1.0f + __builtin_amdgcn_exp2f(x * -1.44269504089f)); }
; __device__ __forceinline__ float siluf_(float x) { return x * __builtin_amdgcn_rcpf(1.0f + __builtin_amdgcn_exp2f(x * -1.44269504089f)); }
; __device__ __forceinline__ f32x2 gelu_pk(f32x2 v) {
;     const f32x2 av = __builtin_elementwise_abs(v), d = av * 0.2316418882f + 1.0f;
;     f32x2 t; t.x = __builtin_amdgcn_rcpf(d.x); t.y = __builtin_amdgcn_rcpf(d.y);
;     f32x2 q = t * 0.5307027145f + (-0.7265760135f); q = q * t + 0.7107068705f; q = q * t + (-0.142248368f); q = q * t + 0.127414796f; q = q * t;
;     const f32x2 s = (v * v) * (-0.72134752044f);
;     f32x2 e; e.x = __builtin_amdgcn_exp2f(s.x); e.y = __builtin_amdgcn_exp2f(s.y);
;     const f32x2 m = v * (q * e), r = v - m;
;     f32x2 o; o.x = v.x < 0.f ? m.x : r.x; o.y = v.y < 0.f ? m.y : r.y; return o;
;     __device__ __forceinline__ void epi_proj(const f32x4 (&acc)[2][2][4][2], const pg8::Unit& u, int wr, int wc, int fr, int fq) const {
;     ...
;                             f32x4 v0 = acc[ai][bj][m][0] * rstd, v1 = acc[ai][bj][m][1] * rstd;
;                             if (slot < 2) {
;                                 f32x2 a = gelu_pk((f32x2){v0[0], v0[1]}), b = gelu_pk((f32x2){v0[2], v0[3]}), c = gelu_pk((f32x2){v1[0], v1[1]}), d = gelu_pk((f32x2){v1[2], v1[3]});
;                                 v0 = (f32x4){a.x, a.y, b.x, b.y}; v1 = (f32x4){c.x, c.y, d.x, d.y};
;                             } else if (slot == 5) {
; #pragma unroll
;                                 for (int j = 0; j < 4; ++j) { v0[j] = siluf_(v0[j]); v1[j] = siluf_(v1[j]); }
;                             } else if (slot >= 6) {
; #pragma unroll
;                                 for (int j = 0; j < 4; ++j) { v0[j] = sigmoidf_(v0[j]); v1[j] = sigmoidf_(v1[j]); }
;                             }
;                             u32x4 w; w.x = cvt_pk_bf16(v0[0], v0[1]); w.y = cvt_pk_bf16(v0[2], v0[3]); w.z = cvt_pk_bf16(v1[0], v1[1]); w.w = cvt_pk_bf16(v1[2], v1[3]);
;                             *(u32x4*)(rowp + bj * 128) = w;
	v_pk_mul_f32 v[138:139], v[2:3], v[128:129] op_sel_hi:[1,0]
	v_pk_mul_f32 v[140:141], v[0:1], v[128:129] op_sel_hi:[1,0]
	v_pk_mul_f32 v[130:131], v[6:7], v[128:129] op_sel_hi:[1,0]
	v_pk_mul_f32 v[132:133], v[4:5], v[128:129] op_sel_hi:[1,0]
	v_lshl_add_u64 v[134:135], v[136:137], 0, s[0:1]
	s_mov_b32 s0, 0x58000
	v_and_b32_e32 v164, 0x7fffffff, v132
	v_and_b32_e32 v167, 0x7fffffff, v140
	v_and_b32_e32 v170, 0x7fffffff, v133
	v_and_b32_e32 v173, 0x7fffffff, v141
	v_and_b32_e32 v176, 0x7fffffff, v130
	v_and_b32_e32 v179, 0x7fffffff, v138
	v_and_b32_e32 v182, 0x7fffffff, v131
	v_and_b32_e32 v185, 0x7fffffff, v139
	v_mul_f32_e32 v165, v132, v132
	v_mul_f32_e32 v168, v140, v140
	v_mul_f32_e32 v171, v133, v133
	v_mul_f32_e32 v174, v141, v141
	v_mul_f32_e32 v177, v130, v130
	v_mul_f32_e32 v180, v138, v138
	v_mul_f32_e32 v183, v131, v131
	v_mul_f32_e32 v186, v139, v139
	v_fma_f32 v164, v164, s14, 1.0
	v_fma_f32 v167, v167, s14, 1.0
	v_fma_f32 v170, v170, s14, 1.0
	v_fma_f32 v173, v173, s14, 1.0
	v_fma_f32 v176, v176, s14, 1.0
	v_fma_f32 v179, v179, s14, 1.0
	v_fma_f32 v182, v182, s14, 1.0
	v_fma_f32 v185, v185, s14, 1.0
	v_mul_f32_e32 v165, s20, v165
	v_mul_f32_e32 v168, s20, v168
	v_mul_f32_e32 v171, s20, v171
	v_mul_f32_e32 v174, s20, v174
	v_mul_f32_e32 v177, s20, v177
	v_mul_f32_e32 v180, s20, v180
	v_mul_f32_e32 v183, s20, v183
	v_mul_f32_e32 v186, s20, v186
	v_rcp_f32_e32 v164, v164
	v_rcp_f32_e32 v167, v167
	v_rcp_f32_e32 v170, v170
	v_rcp_f32_e32 v173, v173
	v_rcp_f32_e32 v176, v176
	v_rcp_f32_e32 v179, v179
	v_rcp_f32_e32 v182, v182
	v_rcp_f32_e32 v185, v185
	s_nop 0
	v_exp_f32_e32 v165, v165
	v_exp_f32_e32 v168, v168
	v_exp_f32_e32 v171, v171
	v_exp_f32_e32 v174, v174
	v_exp_f32_e32 v177, v177
	v_exp_f32_e32 v180, v180
	v_exp_f32_e32 v183, v183
	v_exp_f32_e32 v186, v186
	s_nop 0
	v_fma_f32 v166, v164, s15, v188
	v_fma_f32 v169, v167, s15, v188
	v_fma_f32 v172, v170, s15, v188
	v_fma_f32 v175, v173, s15, v188
	v_fma_f32 v178, v176, s15, v188
	v_fma_f32 v181, v179, s15, v188
	v_fma_f32 v184, v182, s15, v188
	v_fma_f32 v187, v185, s15, v188
	v_fma_f32 v166, v166, v164, v189
	v_fma_f32 v169, v169, v167, v189
	v_fma_f32 v172, v172, v170, v189
	v_fma_f32 v175, v175, v173, v189
	v_fma_f32 v178, v178, v176, v189
	v_fma_f32 v181, v181, v179, v189
	v_fma_f32 v184, v184, v182, v189
	v_fma_f32 v187, v187, v185, v189
	v_fma_f32 v166, v166, v164, v190
	v_fma_f32 v169, v169, v167, v190
	v_fma_f32 v172, v172, v170, v190
	v_fma_f32 v175, v175, v173, v190
	v_fma_f32 v178, v178, v176, v190
	v_fma_f32 v181, v181, v179, v190
	v_fma_f32 v184, v184, v182, v190
	v_fma_f32 v187, v187, v185, v190
	v_fma_f32 v166, v166, v164, v191
	v_fma_f32 v169, v169, v167, v191
	v_fma_f32 v172, v172, v170, v191
	v_fma_f32 v175, v175, v173, v191
	v_fma_f32 v178, v178, v176, v191
	v_fma_f32 v181, v181, v179, v191
	v_fma_f32 v184, v184, v182, v191
	v_fma_f32 v187, v187, v185, v191
	v_mul_f32_e32 v166, v166, v164
	v_mul_f32_e32 v169, v169, v167
	v_mul_f32_e32 v172, v172, v170
	v_mul_f32_e32 v175, v175, v173
	v_mul_f32_e32 v178, v178, v176
	v_mul_f32_e32 v181, v181, v179
	v_mul_f32_e32 v184, v184, v182
	v_mul_f32_e32 v187, v187, v185
	v_mul_f32_e32 v166, v166, v165
	v_mul_f32_e32 v169, v169, v168
	v_mul_f32_e32 v172, v172, v171
	v_mul_f32_e32 v175, v175, v174
	v_mul_f32_e32 v178, v178, v177
	v_mul_f32_e32 v181, v181, v180
	v_mul_f32_e32 v184, v184, v183
	v_mul_f32_e32 v187, v187, v186
	v_mul_f32_e32 v166, v132, v166
	v_mul_f32_e32 v169, v140, v169
	v_mul_f32_e32 v172, v133, v172
	v_mul_f32_e32 v175, v141, v175
	v_mul_f32_e32 v178, v130, v178
	v_mul_f32_e32 v181, v138, v181
	v_mul_f32_e32 v184, v131, v184
	v_mul_f32_e32 v187, v139, v187
	v_sub_f32_e32 v165, v132, v166
	v_sub_f32_e32 v168, v140, v169
	v_sub_f32_e32 v171, v133, v172
	v_sub_f32_e32 v174, v141, v175
	v_sub_f32_e32 v177, v130, v178
	v_sub_f32_e32 v180, v138, v181
	v_sub_f32_e32 v183, v131, v184
	v_sub_f32_e32 v186, v139, v187
	v_cmp_gt_f32_e64 s[100:101], 0, v132
	s_nop 1
	v_cndmask_b32_e64 v132, v165, v166, s[100:101]
	v_cmp_gt_f32_e64 s[100:101], 0, v140
	s_nop 1
	v_cndmask_b32_e64 v140, v168, v169, s[100:101]
	v_cmp_gt_f32_e64 s[100:101], 0, v133
	s_nop 1
	v_cndmask_b32_e64 v133, v171, v172, s[100:101]
	v_cmp_gt_f32_e64 s[100:101], 0, v141
	s_nop 1
	v_cndmask_b32_e64 v141, v174, v175, s[100:101]
	v_cmp_gt_f32_e64 s[100:101], 0, v130
	s_nop 1
	v_cndmask_b32_e64 v130, v177, v178, s[100:101]
	v_cmp_gt_f32_e64 s[100:101], 0, v138
	s_nop 1
	v_cndmask_b32_e64 v138, v180, v181, s[100:101]
	v_cmp_gt_f32_e64 s[100:101], 0, v131
	s_nop 1
	v_cndmask_b32_e64 v131, v183, v184, s[100:101]
	v_cmp_gt_f32_e64 s[100:101], 0, v139
	s_nop 1
	v_cndmask_b32_e64 v139, v186, v187, s[100:101]
	v_mov_b32_e32 v142, v130
	v_mov_b32_e32 v143, v131
	v_add_co_u32_e32 v136, vcc, s0, v136
	v_cvt_pk_bf16_f32 v130, v132, v133
	v_cvt_pk_bf16_f32 v131, v142, v143
	v_cvt_pk_bf16_f32 v132, v140, v141
	v_cvt_pk_bf16_f32 v133, v138, v139
	v_addc_co_u32_e32 v137, vcc, 0, v137, vcc
	global_store_dwordx4 v[136:137], v[130:133], off
	v_pk_mul_f32 v[136:137], v[10:11], v[128:129] op_sel_hi:[1,0]
	s_nop 0
	v_pk_mul_f32 v[130:131], v[14:15], v[128:129] op_sel_hi:[1,0]
	v_pk_mul_f32 v[132:133], v[12:13], v[128:129] op_sel_hi:[1,0]
	v_pk_mul_f32 v[128:129], v[8:9], v[128:129] op_sel_hi:[1,0]
;     __device__ __forceinline__ void epi_proj(const f32x4 (&acc)[2][2][4][2], const pg8::Unit& u, int wr, int wc, int fr, int fq) const {
;     ...
;                     if (u.pn == 32) {
;                         if (wc == 0 && fq < 2) {
;                             const f32x4 v0 = acc[ai][0][m][0] * rstd, v1 = acc[ai][0][m][1] * rstd;
;                             float o8[8] = {v0[0], v0[1], v0[2], v0[3], v1[0], v1[1], v1[2], v1[3]};
; #pragma unroll
;                             for (int h = 0; h < 8; ++h) {
;                                 if (fq == 0) o8[h] = sigmoidf_(o8[h]);
;                                 else { const float xx = o8[h] + dt_bias[l * 8 + h]; const float sp = xx > 20.f ? xx : log1pf(__expf(xx)); o8[h] = -__expf(a_log[l * 8 + h]) * sp; }
;                             }
;                             float* dst = bg + (size_t)r * 16 + 8 * fq;
;                             *(f32x4*)dst = (f32x4){o8[0], o8[1], o8[2], o8[3]}; *(f32x4*)(dst + 4) = (f32x4){o8[4], o8[5], o8[6], o8[7]};
;                         }
;                     } else {
;                         const int slot = u.pn >> 2;
;                         bf16_t* rowp = act + (size_t)slot * SLOT_EL + (size_t)r * 1024 + (colt & 1023);
; #pragma unroll
;                         for (int bj = 0; bj < 2; ++bj) {
;                             f32x4 v0 = acc[ai][bj][m][0] * rstd, v1 = acc[ai][bj][m][1] * rstd;
;                             if (slot < 2) {
;                                 f32x2 a = gelu_pk((f32x2){v0[0], v0[1]}), b = gelu_pk((f32x2){v0[2], v0[3]}), c = gelu_pk((f32x2){v1[0], v1[1]}), d = gelu_pk((f32x2){v1[2], v1[3]});
;                                 v0 = (f32x4){a.x, a.y, b.x, b.y}; v1 = (f32x4){c.x, c.y, d.x, d.y};
;                             } else if (slot == 5) {
; #pragma unroll
;                                 for (int j = 0; j < 4; ++j) { v0[j] = siluf_(v0[j]); v1[j] = siluf_(v1[j]); }
;                             } else if (slot >= 6) {
; #pragma unroll
;                                 for (int j = 0; j < 4; ++j) { v0[j] = sigmoidf_(v0[j]); v1[j] = sigmoidf_(v1[j]); }
;                             }
;                             u32x4 w; w.x = cvt_pk_bf16(v0[0], v0[1]); w.y = cvt_pk_bf16(v0[2], v0[3]); w.z = cvt_pk_bf16(v1[0], v1[1]); w.w = cvt_pk_bf16(v1[2], v1[3]);
;                             *(u32x4*)(rowp + bj * 128) = w;
	v_and_b32_e32 v164, 0x7fffffff, v132
	v_and_b32_e32 v167, 0x7fffffff, v128
	v_and_b32_e32 v170, 0x7fffffff, v129
	v_and_b32_e32 v173, 0x7fffffff, v133
	v_mul_f32_e32 v165, v132, v132
	v_mul_f32_e32 v168, v128, v128
	v_mul_f32_e32 v171, v129, v129
	v_mul_f32_e32 v174, v133, v133
	v_fma_f32 v164, v164, s14, 1.0
	v_fma_f32 v167, v167, s14, 1.0
	v_fma_f32 v170, v170, s14, 1.0
	v_fma_f32 v173, v173, s14, 1.0
	v_mul_f32_e32 v165, s20, v165
	v_mul_f32_e32 v168, s20, v168
	v_mul_f32_e32 v171, s20, v171
	v_mul_f32_e32 v174, s20, v174
	v_rcp_f32_e32 v164, v164
	v_rcp_f32_e32 v167, v167
	v_rcp_f32_e32 v170, v170
	v_rcp_f32_e32 v173, v173
	s_nop 0
	v_exp_f32_e32 v165, v165
	v_exp_f32_e32 v168, v168
	v_exp_f32_e32 v171, v171
	v_exp_f32_e32 v174, v174
	s_nop 0
	v_fma_f32 v166, v164, s15, v188
	v_fma_f32 v169, v167, s15, v188
	v_fma_f32 v172, v170, s15, v188
	v_fma_f32 v175, v173, s15, v188
	v_fma_f32 v166, v166, v164, v189
	v_fma_f32 v169, v169, v167, v189
	v_fma_f32 v172, v172, v170, v189
	v_fma_f32 v175, v175, v173, v189
	v_fma_f32 v166, v166, v164, v190
	v_fma_f32 v169, v169, v167, v190
	v_fma_f32 v172, v172, v170, v190
	v_fma_f32 v175, v175, v173, v190
	v_fma_f32 v166, v166, v164, v191
	v_fma_f32 v169, v169, v167, v191
	v_fma_f32 v172, v172, v170, v191
	v_fma_f32 v175, v175, v173, v191
	v_mul_f32_e32 v166, v166, v164
	v_mul_f32_e32 v169, v169, v167
	v_mul_f32_e32 v172, v172, v170
	v_mul_f32_e32 v175, v175, v173
	v_mul_f32_e32 v166, v166, v165
	v_mul_f32_e32 v169, v169, v168
	v_mul_f32_e32 v172, v172, v171
	v_mul_f32_e32 v175, v175, v174
	v_mul_f32_e32 v166, v132, v166
	v_mul_f32_e32 v169, v128, v169
	v_mul_f32_e32 v172, v129, v172
	v_mul_f32_e32 v175, v133, v175
	v_sub_f32_e32 v165, v132, v166
	v_sub_f32_e32 v168, v128, v169
	v_sub_f32_e32 v171, v129, v172
	v_sub_f32_e32 v174, v133, v175
	v_cmp_gt_f32_e64 s[100:101], 0, v132
	s_nop 1
	v_cndmask_b32_e64 v132, v165, v166, s[100:101]
	v_cmp_gt_f32_e64 s[100:101], 0, v128
	s_nop 1
	v_cndmask_b32_e64 v128, v168, v169, s[100:101]
	v_cmp_gt_f32_e64 s[100:101], 0, v129
	s_nop 1
	v_cndmask_b32_e64 v129, v171, v172, s[100:101]
	v_cmp_gt_f32_e64 s[100:101], 0, v133
	s_nop 1
	v_cndmask_b32_e64 v133, v174, v175, s[100:101]
	v_mov_b32_e32 v138, v128
	v_mov_b32_e32 v139, v129
	v_and_b32_e32 v164, 0x7fffffff, v130
	v_mul_f32_e32 v165, v130, v130
	v_fma_f32 v164, v164, s14, 1.0
	v_mul_f32_e32 v165, s20, v165
	v_rcp_f32_e32 v164, v164
	s_nop 0
	v_exp_f32_e32 v165, v165
	s_nop 0
	v_fma_f32 v166, v164, s15, v188
	v_fma_f32 v166, v166, v164, v189
	v_fma_f32 v166, v166, v164, v190
	v_fma_f32 v166, v166, v164, v191
	v_mul_f32_e32 v166, v166, v164
	v_mul_f32_e32 v166, v166, v165
	v_mul_f32_e32 v166, v130, v166
	v_sub_f32_e32 v165, v130, v166
	v_cmp_gt_f32_e64 s[100:101], 0, v130
	s_nop 1
	v_cndmask_b32_e64 v128, v165, v166, s[100:101]
	v_and_b32_e32 v164, 0x7fffffff, v136
	v_and_b32_e32 v167, 0x7fffffff, v131
	v_mul_f32_e32 v165, v136, v136
	v_mul_f32_e32 v168, v131, v131
	v_fma_f32 v164, v164, s14, 1.0
	v_fma_f32 v167, v167, s14, 1.0
	v_mul_f32_e32 v165, s20, v165
	v_mul_f32_e32 v168, s20, v168
	v_rcp_f32_e32 v164, v164
	v_rcp_f32_e32 v167, v167
	s_nop 0
	v_exp_f32_e32 v165, v165
	v_exp_f32_e32 v168, v168
	s_nop 0
	v_fma_f32 v166, v164, s15, v188
	v_fma_f32 v169, v167, s15, v188
	v_fma_f32 v166, v166, v164, v189
	v_fma_f32 v169, v169, v167, v189
	v_fma_f32 v166, v166, v164, v190
	v_fma_f32 v169, v169, v167, v190
	v_fma_f32 v166, v166, v164, v191
	v_fma_f32 v169, v169, v167, v191
	v_mul_f32_e32 v166, v166, v164
	v_mul_f32_e32 v169, v169, v167
	v_mul_f32_e32 v166, v166, v165
	v_mul_f32_e32 v169, v169, v168
	v_mul_f32_e32 v166, v136, v166
	v_mul_f32_e32 v169, v131, v169
	v_sub_f32_e32 v165, v136, v166
	v_sub_f32_e32 v168, v131, v169
	v_cmp_gt_f32_e64 s[100:101], 0, v136
	s_nop 1
	v_cndmask_b32_e64 v130, v165, v166, s[100:101]
	v_cmp_gt_f32_e64 s[100:101], 0, v131
	s_nop 1
	v_cndmask_b32_e64 v129, v168, v169, s[100:101]
	v_mov_b32_e32 v140, v128
	v_mov_b32_e32 v141, v129
	v_and_b32_e32 v164, 0x7fffffff, v137
	v_mul_f32_e32 v165, v137, v137
	v_fma_f32 v164, v164, s14, 1.0
	v_mul_f32_e32 v165, s20, v165
	v_rcp_f32_e32 v164, v164
	s_nop 0
	v_exp_f32_e32 v165, v165
	s_nop 0
	v_fma_f32 v166, v164, s15, v188
	v_fma_f32 v166, v166, v164, v189
	v_fma_f32 v166, v166, v164, v190
	v_fma_f32 v166, v166, v164, v191
	v_mul_f32_e32 v166, v166, v164
	v_mul_f32_e32 v166, v166, v165
	v_mul_f32_e32 v166, v137, v166
	v_sub_f32_e32 v165, v137, v166
	v_cmp_gt_f32_e64 s[100:101], 0, v137
	s_nop 1
	v_cndmask_b32_e64 v131, v165, v166, s[100:101]
	v_mov_b32_e32 v136, v130
	v_mov_b32_e32 v137, v131
	v_cvt_pk_bf16_f32 v128, v132, v133
	v_cvt_pk_bf16_f32 v129, v140, v141
	v_cvt_pk_bf16_f32 v130, v138, v139
	v_cvt_pk_bf16_f32 v131, v136, v137
	global_store_dwordx4 v[134:135], v[128:131], off offset:256
	s_branch .LBB0_701
.LBB0_1031:
	s_cmp_eq_u32 s88, 32
	s_cbranch_scc1 .Lproj_orig
	s_lshr_b32 s100, s88, 2
	s_cmp_ge_u32 s100, 6
	s_cbranch_scc1 .Lepi_sig
	s_cmp_eq_u32 s100, 5
	s_cbranch_scc1 .Lepi_silu
	s_cmp_lt_u32 s100, 2
	s_cbranch_scc1 .Lepi_gelu
	s_cmp_lt_u32 s100, 2
	s_cbranch_scc1 .Lproj_orig
	s_cmp_gt_u32 s100, 4
	s_cbranch_scc1 .Lproj_orig
	s_and_b32 s101, s13, 15
	s_cmp_eq_u32 s101, 15
	s_cbranch_scc1 .Lproj_orig
	s_cmp_eq_u32 s13, 0x80
	s_cbranch_scc0 .Lepi_plain
